# A3 attention schedule (softmax fully interleaved with own MFMAs) + GEMM k-loop DMA issued right after the freeing barrier (5 GEMM phases)
# speedup vs baseline: 1.0097x; 1.0097x over previous
; #define GBAR() do { asm volatile("s_waitcnt vmcnt(0) lgkmcnt(0)" ::: "memory"); __builtin_amdgcn_s_barrier(); } while (0)
; template <int EPI, bool GUARD>
; DEVI void gemm_tile(const Params& p, const bf16_t* __restrict__ A, int lda, const bf16_t* __restrict__ Bt, int ldb, int K,
;                           int row_base, int row_lo, int row_hi, int tile_n, int layer, int which, char* lds) {
;     ...
;   const int swz = c16 >> 1;
;   int koff[2];
; #pragma unroll
;   for (int ks = 0; ks < 2; ++ks) koff[ks] = ((ks * 4 + q4) ^ swz) << 4;
;   const int arow = (wr * 64 + c16) * 128, brow = 16384 + (wc * 64 + c16) * 128;
;     ...
;   GISSUE(0, 0); GBAR();
;   for (int k0 = 0; k0 < K; k0 += 128) {
;     GISSUE(k0 + 64, 1);
;     KSTEPS(0);
;     GBAR();
;     if (k0 + 128 < K) GISSUE(k0 + 128, 0);
;     KSTEPS(1);
;     GBAR();
;   }
.LBB0_536:
	ds_read_b128 v[82:85], v64 offset:32768
	ds_read_b128 v[86:89], v105 offset:49152
	ds_read_b128 v[90:93], v64 offset:34816
	ds_read_b128 v[94:97], v105 offset:51200
	ds_read_b128 v[108:111], v105 offset:53248
	ds_read_b128 v[112:115], v105 offset:55296
	s_addk_i32 s61, 0x80
	s_waitcnt lgkmcnt(0)
	v_mfma_f32_16x16x32_bf16 v[0:3], v[82:85], v[86:89], v[0:3]
	s_add_u32 s16, s16, 0x100
	s_addc_u32 s17, s17, 0
	s_andn2_b64 vcc, exec, s[18:19]
	v_mfma_f32_16x16x32_bf16 v[4:7], v[82:85], v[94:97], v[4:7]
	v_mfma_f32_16x16x32_bf16 v[8:11], v[82:85], v[108:111], v[8:11]
	v_mfma_f32_16x16x32_bf16 v[12:15], v[82:85], v[112:115], v[12:15]
	v_mfma_f32_16x16x32_bf16 v[16:19], v[90:93], v[86:89], v[16:19]
	v_mfma_f32_16x16x32_bf16 v[20:23], v[90:93], v[94:97], v[20:23]
	v_mfma_f32_16x16x32_bf16 v[24:27], v[90:93], v[108:111], v[24:27]
	v_mfma_f32_16x16x32_bf16 v[28:31], v[90:93], v[112:115], v[28:31]
	ds_read_b128 v[82:85], v64 offset:36864
	ds_read_b128 v[90:93], v64 offset:38912
	s_waitcnt lgkmcnt(0)
	v_mfma_f32_16x16x32_bf16 v[116:119], v[82:85], v[86:89], v[32:35]
	s_nop 2
	ds_read_b128 v[32:35], v106 offset:32768
	v_mfma_f32_16x16x32_bf16 v[120:123], v[82:85], v[94:97], v[36:39]
	v_mfma_f32_16x16x32_bf16 v[124:127], v[82:85], v[108:111], v[40:43]
	v_mfma_f32_16x16x32_bf16 v[82:85], v[82:85], v[112:115], v[44:47]
	v_mfma_f32_16x16x32_bf16 v[86:89], v[90:93], v[86:89], v[48:51]
	v_mfma_f32_16x16x32_bf16 v[94:97], v[90:93], v[94:97], v[52:55]
	v_mfma_f32_16x16x32_bf16 v[108:111], v[90:93], v[108:111], v[56:59]
	v_mfma_f32_16x16x32_bf16 v[90:93], v[90:93], v[112:115], v[60:63]
	ds_read_b128 v[112:115], v107 offset:49152
	ds_read_b128 v[36:39], v106 offset:34816
	ds_read_b128 v[128:131], v107 offset:51200
	ds_read_b128 v[132:135], v107 offset:53248
	ds_read_b128 v[136:139], v107 offset:55296
	s_waitcnt lgkmcnt(0)
	v_mfma_f32_16x16x32_bf16 v[56:59], v[32:35], v[112:115], v[0:3]
	v_mfma_f32_16x16x32_bf16 v[60:63], v[32:35], v[132:135], v[8:11]
	s_nop 1
	ds_read_b128 v[0:3], v106 offset:36864
	ds_read_b128 v[8:11], v106 offset:38912
	s_waitcnt vmcnt(0) lgkmcnt(0)
	s_barrier
	s_cbranch_vccz .Lge0_exit1
	v_mfma_f32_16x16x32_bf16 v[48:51], v[32:35], v[128:131], v[4:7]
	s_add_i32 m0, s45, 0x8000
	v_lshl_add_u64 v[246:247], s[16:17], 0, v[66:67]
	v_lshl_add_u64 v[246:247], v[246:247], 0, s[4:5]
	global_load_lds_dwordx4 v[246:247], off
	v_mfma_f32_16x16x32_bf16 v[52:55], v[32:35], v[136:139], v[12:15]
	s_add_i32 m0, s45, 0xc000
	v_lshl_add_u64 v[246:247], s[16:17], 0, v[74:75]
	v_lshl_add_u64 v[246:247], v[246:247], 0, s[6:7]
	global_load_lds_dwordx4 v[246:247], off
	v_mfma_f32_16x16x32_bf16 v[40:43], v[36:39], v[112:115], v[16:19]
	s_add_i32 m0, s45, 0x8400
	v_lshl_add_u64 v[246:247], s[16:17], 0, v[68:69]
	v_lshl_add_u64 v[246:247], v[246:247], 0, s[4:5]
	global_load_lds_dwordx4 v[246:247], off
	v_mfma_f32_16x16x32_bf16 v[32:35], v[36:39], v[128:131], v[20:23]
	s_add_i32 m0, s45, 0xc400
	v_lshl_add_u64 v[246:247], s[16:17], 0, v[76:77]
	v_lshl_add_u64 v[246:247], v[246:247], 0, s[6:7]
	global_load_lds_dwordx4 v[246:247], off
	v_mfma_f32_16x16x32_bf16 v[44:47], v[36:39], v[132:135], v[24:27]
	s_add_i32 m0, s45, 0x8800
	v_lshl_add_u64 v[246:247], s[16:17], 0, v[70:71]
	v_lshl_add_u64 v[246:247], v[246:247], 0, s[4:5]
	global_load_lds_dwordx4 v[246:247], off
	v_mfma_f32_16x16x32_bf16 v[36:39], v[36:39], v[136:139], v[28:31]
	s_add_i32 m0, s45, 0xc800
	v_lshl_add_u64 v[246:247], s[16:17], 0, v[78:79]
	v_lshl_add_u64 v[246:247], v[246:247], 0, s[6:7]
	global_load_lds_dwordx4 v[246:247], off
	s_waitcnt lgkmcnt(0)
	v_mfma_f32_16x16x32_bf16 v[24:27], v[0:3], v[112:115], v[116:119]
	s_add_i32 m0, s45, 0x8c00
	v_lshl_add_u64 v[246:247], s[16:17], 0, v[72:73]
	v_lshl_add_u64 v[246:247], v[246:247], 0, s[4:5]
	global_load_lds_dwordx4 v[246:247], off
	v_mfma_f32_16x16x32_bf16 v[16:19], v[0:3], v[128:131], v[120:123]
	s_add_i32 m0, s45, 0xcc00
	v_lshl_add_u64 v[246:247], s[16:17], 0, v[80:81]
	v_lshl_add_u64 v[246:247], v[246:247], 0, s[6:7]
	global_load_lds_dwordx4 v[246:247], off
	v_mfma_f32_16x16x32_bf16 v[28:31], v[0:3], v[132:135], v[124:127]
	v_mfma_f32_16x16x32_bf16 v[20:23], v[0:3], v[136:139], v[82:85]
	v_mfma_f32_16x16x32_bf16 v[4:7], v[8:11], v[112:115], v[86:89]
	v_mfma_f32_16x16x32_bf16 v[0:3], v[8:11], v[128:131], v[94:97]
	v_mfma_f32_16x16x32_bf16 v[12:15], v[8:11], v[132:135], v[108:111]
	v_mfma_f32_16x16x32_bf16 v[8:11], v[8:11], v[136:139], v[90:93]
	s_cmpk_gt_u32 s61, 0x37f
	s_branch .Lge0_k0
.Lge0_exit1:
	v_mfma_f32_16x16x32_bf16 v[48:51], v[32:35], v[128:131], v[4:7]
	v_mfma_f32_16x16x32_bf16 v[52:55], v[32:35], v[136:139], v[12:15]
	v_mfma_f32_16x16x32_bf16 v[40:43], v[36:39], v[112:115], v[16:19]
	v_mfma_f32_16x16x32_bf16 v[32:35], v[36:39], v[128:131], v[20:23]
	v_mfma_f32_16x16x32_bf16 v[44:47], v[36:39], v[132:135], v[24:27]
	v_mfma_f32_16x16x32_bf16 v[36:39], v[36:39], v[136:139], v[28:31]
	s_waitcnt lgkmcnt(0)
	v_mfma_f32_16x16x32_bf16 v[24:27], v[0:3], v[112:115], v[116:119]
	v_mfma_f32_16x16x32_bf16 v[16:19], v[0:3], v[128:131], v[120:123]
	v_mfma_f32_16x16x32_bf16 v[28:31], v[0:3], v[132:135], v[124:127]
	v_mfma_f32_16x16x32_bf16 v[20:23], v[0:3], v[136:139], v[82:85]
	v_mfma_f32_16x16x32_bf16 v[4:7], v[8:11], v[112:115], v[86:89]
	v_mfma_f32_16x16x32_bf16 v[0:3], v[8:11], v[128:131], v[94:97]
	v_mfma_f32_16x16x32_bf16 v[12:15], v[8:11], v[132:135], v[108:111]
	v_mfma_f32_16x16x32_bf16 v[8:11], v[8:11], v[136:139], v[90:93]
	s_branch .LBB0_526

; #define GBAR() do { asm volatile("s_waitcnt vmcnt(0) lgkmcnt(0)" ::: "memory"); __builtin_amdgcn_s_barrier(); } while (0)
; template <int EPI, bool GUARD>
; DEVI void gemm_tile(const Params& p, const bf16_t* __restrict__ A, int lda, const bf16_t* __restrict__ Bt, int ldb, int K,
;                           int row_base, int row_lo, int row_hi, int tile_n, int layer, int which, char* lds) {
;     ...
;   const int swz = c16 >> 1;
;   int koff[2];
; #pragma unroll
;   for (int ks = 0; ks < 2; ++ks) koff[ks] = ((ks * 4 + q4) ^ swz) << 4;
;   const int arow = (wr * 64 + c16) * 128, brow = 16384 + (wc * 64 + c16) * 128;
;     ...
;   GISSUE(0, 0); GBAR();
;   for (int k0 = 0; k0 < K; k0 += 128) {
;     GISSUE(k0 + 64, 1);
;     KSTEPS(0);
;     GBAR();
;     if (k0 + 128 < K) GISSUE(k0 + 128, 0);
;     KSTEPS(1);
;     GBAR();
;   }
.Lge0_k0:
	ds_read_b128 v[108:111], v64
	ds_read_b128 v[112:115], v105 offset:16384
	ds_read_b128 v[116:119], v64 offset:2048
	ds_read_b128 v[120:123], v105 offset:18432
	ds_read_b128 v[124:127], v105 offset:20480
	ds_read_b128 v[128:131], v105 offset:22528
	s_waitcnt lgkmcnt(0)
	v_mfma_f32_16x16x32_bf16 v[56:59], v[108:111], v[112:115], v[56:59]
	s_cselect_b64 s[18:19], -1, 0
	s_and_b64 vcc, exec, s[18:19]
	v_mfma_f32_16x16x32_bf16 v[48:51], v[108:111], v[120:123], v[48:51]
	v_mfma_f32_16x16x32_bf16 v[60:63], v[108:111], v[124:127], v[60:63]
	v_mfma_f32_16x16x32_bf16 v[52:55], v[108:111], v[128:131], v[52:55]
	v_mfma_f32_16x16x32_bf16 v[40:43], v[116:119], v[112:115], v[40:43]
	v_mfma_f32_16x16x32_bf16 v[32:35], v[116:119], v[120:123], v[32:35]
	v_mfma_f32_16x16x32_bf16 v[44:47], v[116:119], v[124:127], v[44:47]
	v_mfma_f32_16x16x32_bf16 v[36:39], v[116:119], v[128:131], v[36:39]
	ds_read_b128 v[108:111], v64 offset:4096
	ds_read_b128 v[116:119], v64 offset:6144
	s_waitcnt lgkmcnt(0)
	v_mfma_f32_16x16x32_bf16 v[140:143], v[108:111], v[124:127], v[28:31]
	v_mfma_f32_16x16x32_bf16 v[124:127], v[116:119], v[124:127], v[12:15]
	s_nop 2
	ds_read_b128 v[12:15], v106
	v_mfma_f32_16x16x32_bf16 v[132:135], v[108:111], v[112:115], v[24:27]
	v_mfma_f32_16x16x32_bf16 v[136:139], v[108:111], v[120:123], v[16:19]
	v_mfma_f32_16x16x32_bf16 v[108:111], v[108:111], v[128:131], v[20:23]
	v_mfma_f32_16x16x32_bf16 v[112:115], v[116:119], v[112:115], v[4:7]
	v_mfma_f32_16x16x32_bf16 v[120:123], v[116:119], v[120:123], v[0:3]
	v_mfma_f32_16x16x32_bf16 v[116:119], v[116:119], v[128:131], v[8:11]
	ds_read_b128 v[128:131], v107 offset:16384
	ds_read_b128 v[28:31], v106 offset:2048
	ds_read_b128 v[144:147], v107 offset:18432
	s_waitcnt lgkmcnt(0)
	v_mfma_f32_16x16x32_bf16 v[0:3], v[12:15], v[128:131], v[56:59]
	s_nop 2
	ds_read_b128 v[56:59], v107 offset:20480
	ds_read_b128 v[148:151], v107 offset:22528
	s_waitcnt lgkmcnt(0)
	v_mfma_f32_16x16x32_bf16 v[8:11], v[12:15], v[56:59], v[60:63]
	v_mfma_f32_16x16x32_bf16 v[24:27], v[28:31], v[56:59], v[44:47]
	s_nop 2
	ds_read_b128 v[44:47], v106 offset:4096
	ds_read_b128 v[60:63], v106 offset:6144
	s_waitcnt vmcnt(0) lgkmcnt(0)
	s_barrier
	s_cbranch_vccnz .Lge0_last0
	v_mfma_f32_16x16x32_bf16 v[4:7], v[12:15], v[144:147], v[48:51]
	s_mov_b32 m0, s45
	v_lshl_add_u64 v[246:247], s[16:17], 0, v[66:67]
	v_lshl_add_u64 v[246:247], v[246:247], 0, s[8:9]
	global_load_lds_dwordx4 v[246:247], off
	v_mfma_f32_16x16x32_bf16 v[12:15], v[12:15], v[148:151], v[52:55]
	s_mov_b32 m0, s46
	v_lshl_add_u64 v[246:247], s[16:17], 0, v[74:75]
	v_lshl_add_u64 v[246:247], v[246:247], 0, s[12:13]
	global_load_lds_dwordx4 v[246:247], off
	v_mfma_f32_16x16x32_bf16 v[16:19], v[28:31], v[128:131], v[40:43]
	s_mov_b32 m0, s47
	v_lshl_add_u64 v[246:247], s[16:17], 0, v[68:69]
	v_lshl_add_u64 v[246:247], v[246:247], 0, s[8:9]
	global_load_lds_dwordx4 v[246:247], off
	v_mfma_f32_16x16x32_bf16 v[20:23], v[28:31], v[144:147], v[32:35]
	s_mov_b32 m0, s54
	v_lshl_add_u64 v[246:247], s[16:17], 0, v[76:77]
	v_lshl_add_u64 v[246:247], v[246:247], 0, s[12:13]
	global_load_lds_dwordx4 v[246:247], off
	v_mfma_f32_16x16x32_bf16 v[28:31], v[28:31], v[148:151], v[36:39]
	s_mov_b32 m0, s55
	v_lshl_add_u64 v[246:247], s[16:17], 0, v[70:71]
	v_lshl_add_u64 v[246:247], v[246:247], 0, s[8:9]
	global_load_lds_dwordx4 v[246:247], off
	s_waitcnt lgkmcnt(0)
	v_mfma_f32_16x16x32_bf16 v[32:35], v[44:47], v[128:131], v[132:135]
	s_mov_b32 m0, s58
	v_lshl_add_u64 v[246:247], s[16:17], 0, v[78:79]
	v_lshl_add_u64 v[246:247], v[246:247], 0, s[12:13]
	global_load_lds_dwordx4 v[246:247], off
	v_mfma_f32_16x16x32_bf16 v[36:39], v[44:47], v[144:147], v[136:139]
	s_mov_b32 m0, s59
	v_lshl_add_u64 v[246:247], s[16:17], 0, v[72:73]
	v_lshl_add_u64 v[246:247], v[246:247], 0, s[8:9]
	global_load_lds_dwordx4 v[246:247], off
	v_mfma_f32_16x16x32_bf16 v[40:43], v[44:47], v[56:59], v[140:143]
	s_mov_b32 m0, s60
	v_lshl_add_u64 v[246:247], s[16:17], 0, v[80:81]
	v_lshl_add_u64 v[246:247], v[246:247], 0, s[12:13]
	global_load_lds_dwordx4 v[246:247], off
	v_mfma_f32_16x16x32_bf16 v[44:47], v[44:47], v[148:151], v[108:111]
	v_mfma_f32_16x16x32_bf16 v[48:51], v[60:63], v[128:131], v[112:115]
	v_mfma_f32_16x16x32_bf16 v[52:55], v[60:63], v[144:147], v[120:123]
	v_mfma_f32_16x16x32_bf16 v[56:59], v[60:63], v[56:59], v[124:127]
	v_mfma_f32_16x16x32_bf16 v[60:63], v[60:63], v[148:151], v[116:119]
	s_branch .LBB0_536
.Lge0_last0:
	v_mfma_f32_16x16x32_bf16 v[4:7], v[12:15], v[144:147], v[48:51]
	v_mfma_f32_16x16x32_bf16 v[12:15], v[12:15], v[148:151], v[52:55]
	v_mfma_f32_16x16x32_bf16 v[16:19], v[28:31], v[128:131], v[40:43]
	v_mfma_f32_16x16x32_bf16 v[20:23], v[28:31], v[144:147], v[32:35]
	v_mfma_f32_16x16x32_bf16 v[28:31], v[28:31], v[148:151], v[36:39]
	s_waitcnt lgkmcnt(0)
	v_mfma_f32_16x16x32_bf16 v[32:35], v[44:47], v[128:131], v[132:135]
	v_mfma_f32_16x16x32_bf16 v[36:39], v[44:47], v[144:147], v[136:139]
	v_mfma_f32_16x16x32_bf16 v[40:43], v[44:47], v[56:59], v[140:143]
	v_mfma_f32_16x16x32_bf16 v[44:47], v[44:47], v[148:151], v[108:111]
	v_mfma_f32_16x16x32_bf16 v[48:51], v[60:63], v[128:131], v[112:115]
	v_mfma_f32_16x16x32_bf16 v[52:55], v[60:63], v[144:147], v[120:123]
	v_mfma_f32_16x16x32_bf16 v[56:59], v[60:63], v[56:59], v[124:127]
	v_mfma_f32_16x16x32_bf16 v[60:63], v[60:63], v[148:151], v[116:119]
	s_branch .LBB0_536

; #define GBAR() do { asm volatile("s_waitcnt vmcnt(0) lgkmcnt(0)" ::: "memory"); __builtin_amdgcn_s_barrier(); } while (0)
; template <int EPI, bool GUARD>
; DEVI void gemm_tile(const Params& p, const bf16_t* __restrict__ A, int lda, const bf16_t* __restrict__ Bt, int ldb, int K,
;                           int row_base, int row_lo, int row_hi, int tile_n, int layer, int which, char* lds) {
;     ...
;   const int swz = c16 >> 1;
;   int koff[2];
; #pragma unroll
;   for (int ks = 0; ks < 2; ++ks) koff[ks] = ((ks * 4 + q4) ^ swz) << 4;
;   const int arow = (wr * 64 + c16) * 128, brow = 16384 + (wc * 64 + c16) * 128;
;     ...
;   GISSUE(0, 0); GBAR();
;   for (int k0 = 0; k0 < K; k0 += 128) {
;     GISSUE(k0 + 64, 1);
;     KSTEPS(0);
;     GBAR();
;     if (k0 + 128 < K) GISSUE(k0 + 128, 0);
;     KSTEPS(1);
;     GBAR();
;   }
.LBB0_667:
	ds_read_b128 v[82:85], v64 offset:32768
	ds_read_b128 v[86:89], v111 offset:49152
	ds_read_b128 v[90:93], v64 offset:34816
	ds_read_b128 v[94:97], v111 offset:51200
	ds_read_b128 v[114:117], v111 offset:53248
	ds_read_b128 v[118:121], v111 offset:55296
	s_addk_i32 s9, 0x80
	s_waitcnt lgkmcnt(0)
	v_mfma_f32_16x16x32_bf16 v[0:3], v[82:85], v[86:89], v[0:3]
	s_add_u32 s4, s4, 0x100
	s_addc_u32 s5, s5, 0
	s_and_b64 vcc, exec, s[6:7]
	v_mfma_f32_16x16x32_bf16 v[4:7], v[82:85], v[94:97], v[4:7]
	v_mfma_f32_16x16x32_bf16 v[8:11], v[82:85], v[114:117], v[8:11]
	v_mfma_f32_16x16x32_bf16 v[12:15], v[82:85], v[118:121], v[12:15]
	v_mfma_f32_16x16x32_bf16 v[82:85], v[90:93], v[86:89], v[16:19]
	v_mfma_f32_16x16x32_bf16 v[20:23], v[90:93], v[94:97], v[20:23]
	v_mfma_f32_16x16x32_bf16 v[24:27], v[90:93], v[114:117], v[24:27]
	v_mfma_f32_16x16x32_bf16 v[28:31], v[90:93], v[118:121], v[28:31]
	ds_read_b128 v[16:19], v64 offset:36864
	ds_read_b128 v[90:93], v64 offset:38912
	s_waitcnt lgkmcnt(0)
	v_mfma_f32_16x16x32_bf16 v[122:125], v[16:19], v[86:89], v[32:35]
	v_mfma_f32_16x16x32_bf16 v[36:39], v[16:19], v[94:97], v[36:39]
	v_mfma_f32_16x16x32_bf16 v[40:43], v[16:19], v[114:117], v[40:43]
	v_mfma_f32_16x16x32_bf16 v[44:47], v[16:19], v[118:121], v[44:47]
	ds_read_b128 v[16:19], v112 offset:32768
	v_mfma_f32_16x16x32_bf16 v[86:89], v[90:93], v[86:89], v[48:51]
	v_mfma_f32_16x16x32_bf16 v[52:55], v[90:93], v[94:97], v[52:55]
	v_mfma_f32_16x16x32_bf16 v[56:59], v[90:93], v[114:117], v[56:59]
	v_mfma_f32_16x16x32_bf16 v[60:63], v[90:93], v[118:121], v[60:63]
	ds_read_b128 v[90:93], v113 offset:49152
	ds_read_b128 v[32:35], v112 offset:34816
	ds_read_b128 v[94:97], v113 offset:51200
	ds_read_b128 v[114:117], v113 offset:53248
	ds_read_b128 v[118:121], v113 offset:55296
	s_waitcnt lgkmcnt(0)
	v_mfma_f32_16x16x32_bf16 v[0:3], v[16:19], v[90:93], v[0:3]
	v_mfma_f32_16x16x32_bf16 v[4:7], v[16:19], v[94:97], v[4:7]
	v_mfma_f32_16x16x32_bf16 v[8:11], v[16:19], v[114:117], v[8:11]
	v_mfma_f32_16x16x32_bf16 v[16:19], v[16:19], v[118:121], v[12:15]
	v_mfma_f32_16x16x32_bf16 v[12:15], v[32:35], v[90:93], v[82:85]
	ds_read_b128 v[48:51], v112 offset:36864
	s_nop 1
	ds_read_b128 v[82:85], v112 offset:38912
	s_waitcnt vmcnt(0) lgkmcnt(0)
	s_barrier
	s_cbranch_vccnz .Lge1_exit1
	v_mfma_f32_16x16x32_bf16 v[20:23], v[32:35], v[94:97], v[20:23]
	s_add_i32 m0, s69, 0x8000
	v_lshl_add_u64 v[246:247], s[4:5], 0, v[66:67]
	v_lshl_add_u64 v[246:247], v[246:247], 0, s[16:17]
	global_load_lds_dwordx4 v[246:247], off
	v_mfma_f32_16x16x32_bf16 v[24:27], v[32:35], v[114:117], v[24:27]
	s_add_i32 m0, s69, 0xc000
	v_lshl_add_u64 v[246:247], s[4:5], 0, v[74:75]
	v_lshl_add_u64 v[246:247], v[246:247], 0, s[18:19]
	global_load_lds_dwordx4 v[246:247], off
	v_mfma_f32_16x16x32_bf16 v[32:35], v[32:35], v[118:121], v[28:31]
	s_add_i32 m0, s69, 0x8400
	v_lshl_add_u64 v[246:247], s[4:5], 0, v[68:69]
	v_lshl_add_u64 v[246:247], v[246:247], 0, s[16:17]
	global_load_lds_dwordx4 v[246:247], off
	s_waitcnt lgkmcnt(0)
	v_mfma_f32_16x16x32_bf16 v[28:31], v[48:51], v[90:93], v[122:125]
	s_add_i32 m0, s69, 0xc400
	v_lshl_add_u64 v[246:247], s[4:5], 0, v[76:77]
	v_lshl_add_u64 v[246:247], v[246:247], 0, s[18:19]
	global_load_lds_dwordx4 v[246:247], off
	v_mfma_f32_16x16x32_bf16 v[36:39], v[48:51], v[94:97], v[36:39]
	s_add_i32 m0, s69, 0x8800
	v_lshl_add_u64 v[246:247], s[4:5], 0, v[70:71]
	v_lshl_add_u64 v[246:247], v[246:247], 0, s[16:17]
	global_load_lds_dwordx4 v[246:247], off
	v_mfma_f32_16x16x32_bf16 v[40:43], v[48:51], v[114:117], v[40:43]
	s_add_i32 m0, s69, 0xc800
	v_lshl_add_u64 v[246:247], s[4:5], 0, v[78:79]
	v_lshl_add_u64 v[246:247], v[246:247], 0, s[18:19]
	global_load_lds_dwordx4 v[246:247], off
	v_mfma_f32_16x16x32_bf16 v[48:51], v[48:51], v[118:121], v[44:47]
	s_add_i32 m0, s75, 0x8000
	v_lshl_add_u64 v[246:247], s[4:5], 0, v[72:73]
	v_lshl_add_u64 v[246:247], v[246:247], 0, s[16:17]
	global_load_lds_dwordx4 v[246:247], off
	v_mfma_f32_16x16x32_bf16 v[44:47], v[82:85], v[90:93], v[86:89]
	s_add_i32 m0, s75, 0xc000
	v_lshl_add_u64 v[246:247], s[4:5], 0, v[80:81]
	v_lshl_add_u64 v[246:247], v[246:247], 0, s[18:19]
	global_load_lds_dwordx4 v[246:247], off
	v_mfma_f32_16x16x32_bf16 v[52:55], v[82:85], v[94:97], v[52:55]
	v_mfma_f32_16x16x32_bf16 v[56:59], v[82:85], v[114:117], v[56:59]
	v_mfma_f32_16x16x32_bf16 v[60:63], v[82:85], v[118:121], v[60:63]
	s_cmpk_gt_u32 s9, 0x37f
	s_branch .Lge1_k0
.Lge1_exit1:
	v_mfma_f32_16x16x32_bf16 v[20:23], v[32:35], v[94:97], v[20:23]
	v_mfma_f32_16x16x32_bf16 v[24:27], v[32:35], v[114:117], v[24:27]
	v_mfma_f32_16x16x32_bf16 v[32:35], v[32:35], v[118:121], v[28:31]
	s_waitcnt lgkmcnt(0)
	v_mfma_f32_16x16x32_bf16 v[28:31], v[48:51], v[90:93], v[122:125]
	v_mfma_f32_16x16x32_bf16 v[36:39], v[48:51], v[94:97], v[36:39]
	v_mfma_f32_16x16x32_bf16 v[40:43], v[48:51], v[114:117], v[40:43]
	v_mfma_f32_16x16x32_bf16 v[48:51], v[48:51], v[118:121], v[44:47]
	v_mfma_f32_16x16x32_bf16 v[44:47], v[82:85], v[90:93], v[86:89]
	v_mfma_f32_16x16x32_bf16 v[52:55], v[82:85], v[94:97], v[52:55]
	v_mfma_f32_16x16x32_bf16 v[56:59], v[82:85], v[114:117], v[56:59]
	v_mfma_f32_16x16x32_bf16 v[60:63], v[82:85], v[118:121], v[60:63]
	s_branch .LBB0_670

; #define GBAR() do { asm volatile("s_waitcnt vmcnt(0) lgkmcnt(0)" ::: "memory"); __builtin_amdgcn_s_barrier(); } while (0)
; template <int EPI, bool GUARD>
; DEVI void gemm_tile(const Params& p, const bf16_t* __restrict__ A, int lda, const bf16_t* __restrict__ Bt, int ldb, int K,
;                           int row_base, int row_lo, int row_hi, int tile_n, int layer, int which, char* lds) {
;     ...
;   const int swz = c16 >> 1;
;   int koff[2];
; #pragma unroll
;   for (int ks = 0; ks < 2; ++ks) koff[ks] = ((ks * 4 + q4) ^ swz) << 4;
;   const int arow = (wr * 64 + c16) * 128, brow = 16384 + (wc * 64 + c16) * 128;
;     ...
;   GISSUE(0, 0); GBAR();
;   for (int k0 = 0; k0 < K; k0 += 128) {
;     GISSUE(k0 + 64, 1);
;     KSTEPS(0);
;     GBAR();
;     if (k0 + 128 < K) GISSUE(k0 + 128, 0);
;     KSTEPS(1);
;     GBAR();
;   }
.Lge1_k0:
	ds_read_b128 v[114:117], v64
	ds_read_b128 v[118:121], v111 offset:16384
	ds_read_b128 v[122:125], v64 offset:2048
	ds_read_b128 v[126:129], v111 offset:18432
	ds_read_b128 v[130:133], v111 offset:20480
	ds_read_b128 v[134:137], v111 offset:22528
	s_waitcnt lgkmcnt(0)
	v_mfma_f32_16x16x32_bf16 v[0:3], v[114:117], v[118:121], v[0:3]
	s_cselect_b64 s[6:7], -1, 0
	s_and_b64 vcc, exec, s[6:7]
	v_mfma_f32_16x16x32_bf16 v[4:7], v[114:117], v[126:129], v[4:7]
	v_mfma_f32_16x16x32_bf16 v[8:11], v[114:117], v[130:133], v[8:11]
	v_mfma_f32_16x16x32_bf16 v[16:19], v[114:117], v[134:137], v[16:19]
	v_mfma_f32_16x16x32_bf16 v[114:117], v[122:125], v[118:121], v[12:15]
	v_mfma_f32_16x16x32_bf16 v[20:23], v[122:125], v[126:129], v[20:23]
	v_mfma_f32_16x16x32_bf16 v[24:27], v[122:125], v[130:133], v[24:27]
	v_mfma_f32_16x16x32_bf16 v[32:35], v[122:125], v[134:137], v[32:35]
	ds_read_b128 v[12:15], v64 offset:4096
	ds_read_b128 v[122:125], v64 offset:6144
	s_waitcnt lgkmcnt(0)
	v_mfma_f32_16x16x32_bf16 v[138:141], v[12:15], v[118:121], v[28:31]
	v_mfma_f32_16x16x32_bf16 v[36:39], v[12:15], v[126:129], v[36:39]
	v_mfma_f32_16x16x32_bf16 v[40:43], v[12:15], v[130:133], v[40:43]
	v_mfma_f32_16x16x32_bf16 v[48:51], v[12:15], v[134:137], v[48:51]
	ds_read_b128 v[12:15], v112
	v_mfma_f32_16x16x32_bf16 v[118:121], v[122:125], v[118:121], v[44:47]
	v_mfma_f32_16x16x32_bf16 v[52:55], v[122:125], v[126:129], v[52:55]
	v_mfma_f32_16x16x32_bf16 v[56:59], v[122:125], v[130:133], v[56:59]
	v_mfma_f32_16x16x32_bf16 v[60:63], v[122:125], v[134:137], v[60:63]
	ds_read_b128 v[122:125], v113 offset:16384
	ds_read_b128 v[28:31], v112 offset:2048
	ds_read_b128 v[126:129], v113 offset:18432
	ds_read_b128 v[130:133], v113 offset:20480
	ds_read_b128 v[134:137], v113 offset:22528
	s_waitcnt lgkmcnt(0)
	v_mfma_f32_16x16x32_bf16 v[0:3], v[12:15], v[122:125], v[0:3]
	v_mfma_f32_16x16x32_bf16 v[4:7], v[12:15], v[126:129], v[4:7]
	v_mfma_f32_16x16x32_bf16 v[8:11], v[12:15], v[130:133], v[8:11]
	v_mfma_f32_16x16x32_bf16 v[12:15], v[12:15], v[134:137], v[16:19]
	v_mfma_f32_16x16x32_bf16 v[16:19], v[28:31], v[122:125], v[114:117]
	ds_read_b128 v[44:47], v112 offset:4096
	s_nop 1
	ds_read_b128 v[114:117], v112 offset:6144
	s_waitcnt vmcnt(0) lgkmcnt(0)
	s_barrier
	s_cbranch_vccnz .Lge1_last0
	v_mfma_f32_16x16x32_bf16 v[20:23], v[28:31], v[126:129], v[20:23]
	s_mov_b32 m0, s69
	v_lshl_add_u64 v[246:247], s[4:5], 0, v[66:67]
	v_lshl_add_u64 v[246:247], v[246:247], 0, s[26:27]
	global_load_lds_dwordx4 v[246:247], off
	v_mfma_f32_16x16x32_bf16 v[24:27], v[28:31], v[130:133], v[24:27]
	s_mov_b32 m0, s70
	v_lshl_add_u64 v[246:247], s[4:5], 0, v[74:75]
	v_lshl_add_u64 v[246:247], v[246:247], 0, s[34:35]
	global_load_lds_dwordx4 v[246:247], off
	v_mfma_f32_16x16x32_bf16 v[28:31], v[28:31], v[134:137], v[32:35]
	s_mov_b32 m0, s71
	v_lshl_add_u64 v[246:247], s[4:5], 0, v[68:69]
	v_lshl_add_u64 v[246:247], v[246:247], 0, s[26:27]
	global_load_lds_dwordx4 v[246:247], off
	s_waitcnt lgkmcnt(0)
	v_mfma_f32_16x16x32_bf16 v[32:35], v[44:47], v[122:125], v[138:141]
	s_mov_b32 m0, s72
	v_lshl_add_u64 v[246:247], s[4:5], 0, v[76:77]
	v_lshl_add_u64 v[246:247], v[246:247], 0, s[34:35]
	global_load_lds_dwordx4 v[246:247], off
	v_mfma_f32_16x16x32_bf16 v[36:39], v[44:47], v[126:129], v[36:39]
	s_mov_b32 m0, s73
	v_lshl_add_u64 v[246:247], s[4:5], 0, v[70:71]
	v_lshl_add_u64 v[246:247], v[246:247], 0, s[26:27]
	global_load_lds_dwordx4 v[246:247], off
	v_mfma_f32_16x16x32_bf16 v[40:43], v[44:47], v[130:133], v[40:43]
	s_mov_b32 m0, s74
	v_lshl_add_u64 v[246:247], s[4:5], 0, v[78:79]
	v_lshl_add_u64 v[246:247], v[246:247], 0, s[34:35]
	global_load_lds_dwordx4 v[246:247], off
	v_mfma_f32_16x16x32_bf16 v[44:47], v[44:47], v[134:137], v[48:51]
	s_mov_b32 m0, s75
	v_lshl_add_u64 v[246:247], s[4:5], 0, v[72:73]
	v_lshl_add_u64 v[246:247], v[246:247], 0, s[26:27]
	global_load_lds_dwordx4 v[246:247], off
	v_mfma_f32_16x16x32_bf16 v[48:51], v[114:117], v[122:125], v[118:121]
	s_mov_b32 m0, s76
	v_lshl_add_u64 v[246:247], s[4:5], 0, v[80:81]
	v_lshl_add_u64 v[246:247], v[246:247], 0, s[34:35]
	global_load_lds_dwordx4 v[246:247], off
	v_mfma_f32_16x16x32_bf16 v[52:55], v[114:117], v[126:129], v[52:55]
	v_mfma_f32_16x16x32_bf16 v[56:59], v[114:117], v[130:133], v[56:59]
	v_mfma_f32_16x16x32_bf16 v[60:63], v[114:117], v[134:137], v[60:63]
	s_branch .LBB0_667
.Lge1_last0:
	v_mfma_f32_16x16x32_bf16 v[20:23], v[28:31], v[126:129], v[20:23]
	v_mfma_f32_16x16x32_bf16 v[24:27], v[28:31], v[130:133], v[24:27]
	v_mfma_f32_16x16x32_bf16 v[28:31], v[28:31], v[134:137], v[32:35]
	s_waitcnt lgkmcnt(0)
	v_mfma_f32_16x16x32_bf16 v[32:35], v[44:47], v[122:125], v[138:141]
	v_mfma_f32_16x16x32_bf16 v[36:39], v[44:47], v[126:129], v[36:39]
	v_mfma_f32_16x16x32_bf16 v[40:43], v[44:47], v[130:133], v[40:43]
	v_mfma_f32_16x16x32_bf16 v[44:47], v[44:47], v[134:137], v[48:51]
	v_mfma_f32_16x16x32_bf16 v[48:51], v[114:117], v[122:125], v[118:121]
	v_mfma_f32_16x16x32_bf16 v[52:55], v[114:117], v[126:129], v[52:55]
	v_mfma_f32_16x16x32_bf16 v[56:59], v[114:117], v[130:133], v[56:59]
	v_mfma_f32_16x16x32_bf16 v[60:63], v[114:117], v[134:137], v[60:63]
	s_branch .LBB0_667

; #define GBAR() do { asm volatile("s_waitcnt vmcnt(0) lgkmcnt(0)" ::: "memory"); __builtin_amdgcn_s_barrier(); } while (0)
; template <int EPI, bool GUARD>
; DEVI void gemm_tile(const Params& p, const bf16_t* __restrict__ A, int lda, const bf16_t* __restrict__ Bt, int ldb, int K,
;                           int row_base, int row_lo, int row_hi, int tile_n, int layer, int which, char* lds) {
;     ...
;   const int swz = c16 >> 1;
;   int koff[2];
; #pragma unroll
;   for (int ks = 0; ks < 2; ++ks) koff[ks] = ((ks * 4 + q4) ^ swz) << 4;
;   const int arow = (wr * 64 + c16) * 128, brow = 16384 + (wc * 64 + c16) * 128;
;     ...
;   GISSUE(0, 0); GBAR();
;   for (int k0 = 0; k0 < K; k0 += 128) {
;     GISSUE(k0 + 64, 1);
;     KSTEPS(0);
;     GBAR();
;     if (k0 + 128 < K) GISSUE(k0 + 128, 0);
;     KSTEPS(1);
;     GBAR();
;   }
.LBB0_878:
	ds_read_b128 v[80:83], v101 offset:32768
	ds_read_b128 v[84:87], v102 offset:49152
	ds_read_b128 v[88:91], v101 offset:34816
	ds_read_b128 v[92:95], v102 offset:51200
	ds_read_b128 v[106:109], v102 offset:53248
	ds_read_b128 v[110:113], v102 offset:55296
	s_addk_i32 s85, 0x80
	s_waitcnt lgkmcnt(0)
	v_mfma_f32_16x16x32_bf16 v[0:3], v[80:83], v[84:87], v[0:3]
	s_add_u32 s4, s4, 0x100
	s_addc_u32 s5, s5, 0
	s_and_b64 vcc, exec, s[52:53]
	v_mfma_f32_16x16x32_bf16 v[4:7], v[80:83], v[92:95], v[4:7]
	v_mfma_f32_16x16x32_bf16 v[8:11], v[80:83], v[106:109], v[8:11]
	v_mfma_f32_16x16x32_bf16 v[12:15], v[80:83], v[110:113], v[12:15]
	v_mfma_f32_16x16x32_bf16 v[80:83], v[88:91], v[84:87], v[16:19]
	v_mfma_f32_16x16x32_bf16 v[20:23], v[88:91], v[92:95], v[20:23]
	v_mfma_f32_16x16x32_bf16 v[24:27], v[88:91], v[106:109], v[24:27]
	v_mfma_f32_16x16x32_bf16 v[28:31], v[88:91], v[110:113], v[28:31]
	ds_read_b128 v[16:19], v101 offset:36864
	ds_read_b128 v[88:91], v101 offset:38912
	s_waitcnt lgkmcnt(0)
	v_mfma_f32_16x16x32_bf16 v[114:117], v[16:19], v[84:87], v[32:35]
	v_mfma_f32_16x16x32_bf16 v[36:39], v[16:19], v[92:95], v[36:39]
	v_mfma_f32_16x16x32_bf16 v[40:43], v[16:19], v[106:109], v[40:43]
	v_mfma_f32_16x16x32_bf16 v[44:47], v[16:19], v[110:113], v[44:47]
	ds_read_b128 v[16:19], v103 offset:32768
	v_mfma_f32_16x16x32_bf16 v[84:87], v[88:91], v[84:87], v[48:51]
	v_mfma_f32_16x16x32_bf16 v[52:55], v[88:91], v[92:95], v[52:55]
	v_mfma_f32_16x16x32_bf16 v[56:59], v[88:91], v[106:109], v[56:59]
	v_mfma_f32_16x16x32_bf16 v[60:63], v[88:91], v[110:113], v[60:63]
	ds_read_b128 v[88:91], v104 offset:49152
	ds_read_b128 v[32:35], v103 offset:34816
	ds_read_b128 v[92:95], v104 offset:51200
	ds_read_b128 v[106:109], v104 offset:53248
	ds_read_b128 v[110:113], v104 offset:55296
	s_waitcnt lgkmcnt(0)
	v_mfma_f32_16x16x32_bf16 v[0:3], v[16:19], v[88:91], v[0:3]
	v_mfma_f32_16x16x32_bf16 v[4:7], v[16:19], v[92:95], v[4:7]
	v_mfma_f32_16x16x32_bf16 v[8:11], v[16:19], v[106:109], v[8:11]
	v_mfma_f32_16x16x32_bf16 v[16:19], v[16:19], v[110:113], v[12:15]
	v_mfma_f32_16x16x32_bf16 v[12:15], v[32:35], v[88:91], v[80:83]
	ds_read_b128 v[48:51], v103 offset:36864
	s_nop 1
	ds_read_b128 v[80:83], v103 offset:38912
	s_waitcnt vmcnt(0) lgkmcnt(0)
	s_barrier
	s_cbranch_vccnz .Lge3_exit1
	v_mfma_f32_16x16x32_bf16 v[20:23], v[32:35], v[92:95], v[20:23]
	s_add_i32 m0, s72, 0x8000
	v_lshl_add_u64 v[246:247], s[4:5], 0, v[64:65]
	v_lshl_add_u64 v[246:247], v[246:247], 0, s[16:17]
	global_load_lds_dwordx4 v[246:247], off
	v_mfma_f32_16x16x32_bf16 v[24:27], v[32:35], v[106:109], v[24:27]
	s_add_i32 m0, s72, 0xc000
	v_lshl_add_u64 v[246:247], s[4:5], 0, v[72:73]
	v_lshl_add_u64 v[246:247], v[246:247], 0, s[18:19]
	global_load_lds_dwordx4 v[246:247], off
	v_mfma_f32_16x16x32_bf16 v[32:35], v[32:35], v[110:113], v[28:31]
	s_add_i32 m0, s72, 0x8400
	v_lshl_add_u64 v[246:247], s[4:5], 0, v[66:67]
	v_lshl_add_u64 v[246:247], v[246:247], 0, s[16:17]
	global_load_lds_dwordx4 v[246:247], off
	s_waitcnt lgkmcnt(0)
	v_mfma_f32_16x16x32_bf16 v[28:31], v[48:51], v[88:91], v[114:117]
	s_add_i32 m0, s72, 0xc400
	v_lshl_add_u64 v[246:247], s[4:5], 0, v[74:75]
	v_lshl_add_u64 v[246:247], v[246:247], 0, s[18:19]
	global_load_lds_dwordx4 v[246:247], off
	v_mfma_f32_16x16x32_bf16 v[36:39], v[48:51], v[92:95], v[36:39]
	s_add_i32 m0, s72, 0x8800
	v_lshl_add_u64 v[246:247], s[4:5], 0, v[68:69]
	v_lshl_add_u64 v[246:247], v[246:247], 0, s[16:17]
	global_load_lds_dwordx4 v[246:247], off
	v_mfma_f32_16x16x32_bf16 v[40:43], v[48:51], v[106:109], v[40:43]
	s_add_i32 m0, s72, 0xc800
	v_lshl_add_u64 v[246:247], s[4:5], 0, v[76:77]
	v_lshl_add_u64 v[246:247], v[246:247], 0, s[18:19]
	global_load_lds_dwordx4 v[246:247], off
	v_mfma_f32_16x16x32_bf16 v[48:51], v[48:51], v[110:113], v[44:47]
	s_add_i32 m0, s78, 0x8000
	v_lshl_add_u64 v[246:247], s[4:5], 0, v[70:71]
	v_lshl_add_u64 v[246:247], v[246:247], 0, s[16:17]
	global_load_lds_dwordx4 v[246:247], off
	v_mfma_f32_16x16x32_bf16 v[44:47], v[80:83], v[88:91], v[84:87]
	s_add_i32 m0, s78, 0xc000
	v_lshl_add_u64 v[246:247], s[4:5], 0, v[78:79]
	v_lshl_add_u64 v[246:247], v[246:247], 0, s[18:19]
	global_load_lds_dwordx4 v[246:247], off
	v_mfma_f32_16x16x32_bf16 v[52:55], v[80:83], v[92:95], v[52:55]
	v_mfma_f32_16x16x32_bf16 v[56:59], v[80:83], v[106:109], v[56:59]
	v_mfma_f32_16x16x32_bf16 v[60:63], v[80:83], v[110:113], v[60:63]
	s_cmpk_gt_u32 s85, 0x37f
	s_branch .Lge3_k0
.Lge3_exit1:
	v_mfma_f32_16x16x32_bf16 v[20:23], v[32:35], v[92:95], v[20:23]
	v_mfma_f32_16x16x32_bf16 v[24:27], v[32:35], v[106:109], v[24:27]
	v_mfma_f32_16x16x32_bf16 v[32:35], v[32:35], v[110:113], v[28:31]
	s_waitcnt lgkmcnt(0)
	v_mfma_f32_16x16x32_bf16 v[28:31], v[48:51], v[88:91], v[114:117]
	v_mfma_f32_16x16x32_bf16 v[36:39], v[48:51], v[92:95], v[36:39]
	v_mfma_f32_16x16x32_bf16 v[40:43], v[48:51], v[106:109], v[40:43]
	v_mfma_f32_16x16x32_bf16 v[48:51], v[48:51], v[110:113], v[44:47]
	v_mfma_f32_16x16x32_bf16 v[44:47], v[80:83], v[88:91], v[84:87]
	v_mfma_f32_16x16x32_bf16 v[52:55], v[80:83], v[92:95], v[52:55]
	v_mfma_f32_16x16x32_bf16 v[56:59], v[80:83], v[106:109], v[56:59]
	v_mfma_f32_16x16x32_bf16 v[60:63], v[80:83], v[110:113], v[60:63]
	s_branch .LBB0_881

; #define GBAR() do { asm volatile("s_waitcnt vmcnt(0) lgkmcnt(0)" ::: "memory"); __builtin_amdgcn_s_barrier(); } while (0)
; template <int EPI, bool GUARD>
; DEVI void gemm_tile(const Params& p, const bf16_t* __restrict__ A, int lda, const bf16_t* __restrict__ Bt, int ldb, int K,
;                           int row_base, int row_lo, int row_hi, int tile_n, int layer, int which, char* lds) {
;     ...
;   const int swz = c16 >> 1;
;   int koff[2];
; #pragma unroll
;   for (int ks = 0; ks < 2; ++ks) koff[ks] = ((ks * 4 + q4) ^ swz) << 4;
;   const int arow = (wr * 64 + c16) * 128, brow = 16384 + (wc * 64 + c16) * 128;
;     ...
;   GISSUE(0, 0); GBAR();
;   for (int k0 = 0; k0 < K; k0 += 128) {
;     GISSUE(k0 + 64, 1);
;     KSTEPS(0);
;     GBAR();
;     if (k0 + 128 < K) GISSUE(k0 + 128, 0);
;     KSTEPS(1);
;     GBAR();
;   }
.Lge3_k0:
	ds_read_b128 v[106:109], v101
	ds_read_b128 v[110:113], v102 offset:16384
	ds_read_b128 v[114:117], v101 offset:2048
	ds_read_b128 v[118:121], v102 offset:18432
	ds_read_b128 v[122:125], v102 offset:20480
	ds_read_b128 v[130:133], v102 offset:22528
	s_waitcnt lgkmcnt(0)
	v_mfma_f32_16x16x32_bf16 v[0:3], v[106:109], v[110:113], v[0:3]
	s_cselect_b64 s[52:53], -1, 0
	s_and_b64 vcc, exec, s[52:53]
	v_mfma_f32_16x16x32_bf16 v[4:7], v[106:109], v[118:121], v[4:7]
	v_mfma_f32_16x16x32_bf16 v[8:11], v[106:109], v[122:125], v[8:11]
	v_mfma_f32_16x16x32_bf16 v[16:19], v[106:109], v[130:133], v[16:19]
	v_mfma_f32_16x16x32_bf16 v[106:109], v[114:117], v[110:113], v[12:15]
	v_mfma_f32_16x16x32_bf16 v[20:23], v[114:117], v[118:121], v[20:23]
	v_mfma_f32_16x16x32_bf16 v[24:27], v[114:117], v[122:125], v[24:27]
	v_mfma_f32_16x16x32_bf16 v[32:35], v[114:117], v[130:133], v[32:35]
	ds_read_b128 v[12:15], v101 offset:4096
	ds_read_b128 v[114:117], v101 offset:6144
	s_waitcnt lgkmcnt(0)
	v_mfma_f32_16x16x32_bf16 v[140:143], v[12:15], v[110:113], v[28:31]
	v_mfma_f32_16x16x32_bf16 v[36:39], v[12:15], v[118:121], v[36:39]
	v_mfma_f32_16x16x32_bf16 v[40:43], v[12:15], v[122:125], v[40:43]
	v_mfma_f32_16x16x32_bf16 v[48:51], v[12:15], v[130:133], v[48:51]
	ds_read_b128 v[12:15], v103
	v_mfma_f32_16x16x32_bf16 v[110:113], v[114:117], v[110:113], v[44:47]
	v_mfma_f32_16x16x32_bf16 v[52:55], v[114:117], v[118:121], v[52:55]
	v_mfma_f32_16x16x32_bf16 v[56:59], v[114:117], v[122:125], v[56:59]
	v_mfma_f32_16x16x32_bf16 v[60:63], v[114:117], v[130:133], v[60:63]
	ds_read_b128 v[114:117], v104 offset:16384
	ds_read_b128 v[28:31], v103 offset:2048
	ds_read_b128 v[118:121], v104 offset:18432
	ds_read_b128 v[122:125], v104 offset:20480
	ds_read_b128 v[130:133], v104 offset:22528
	s_waitcnt lgkmcnt(0)
	v_mfma_f32_16x16x32_bf16 v[0:3], v[12:15], v[114:117], v[0:3]
	v_mfma_f32_16x16x32_bf16 v[4:7], v[12:15], v[118:121], v[4:7]
	v_mfma_f32_16x16x32_bf16 v[8:11], v[12:15], v[122:125], v[8:11]
	v_mfma_f32_16x16x32_bf16 v[12:15], v[12:15], v[130:133], v[16:19]
	v_mfma_f32_16x16x32_bf16 v[16:19], v[28:31], v[114:117], v[106:109]
	ds_read_b128 v[44:47], v103 offset:4096
	s_nop 1
	ds_read_b128 v[106:109], v103 offset:6144
	s_waitcnt vmcnt(0) lgkmcnt(0)
	s_barrier
	s_cbranch_vccnz .Lge3_last0
	v_mfma_f32_16x16x32_bf16 v[20:23], v[28:31], v[118:121], v[20:23]
	s_mov_b32 m0, s72
	v_lshl_add_u64 v[246:247], s[4:5], 0, v[64:65]
	v_lshl_add_u64 v[246:247], v[246:247], 0, s[26:27]
	global_load_lds_dwordx4 v[246:247], off
	v_mfma_f32_16x16x32_bf16 v[24:27], v[28:31], v[122:125], v[24:27]
	s_mov_b32 m0, s73
	v_lshl_add_u64 v[246:247], s[4:5], 0, v[72:73]
	v_lshl_add_u64 v[246:247], v[246:247], 0, s[34:35]
	global_load_lds_dwordx4 v[246:247], off
	v_mfma_f32_16x16x32_bf16 v[28:31], v[28:31], v[130:133], v[32:35]
	s_mov_b32 m0, s74
	v_lshl_add_u64 v[246:247], s[4:5], 0, v[66:67]
	v_lshl_add_u64 v[246:247], v[246:247], 0, s[26:27]
	global_load_lds_dwordx4 v[246:247], off
	s_waitcnt lgkmcnt(0)
	v_mfma_f32_16x16x32_bf16 v[32:35], v[44:47], v[114:117], v[140:143]
	s_mov_b32 m0, s75
	v_lshl_add_u64 v[246:247], s[4:5], 0, v[74:75]
	v_lshl_add_u64 v[246:247], v[246:247], 0, s[34:35]
	global_load_lds_dwordx4 v[246:247], off
	v_mfma_f32_16x16x32_bf16 v[36:39], v[44:47], v[118:121], v[36:39]
	s_mov_b32 m0, s76
	v_lshl_add_u64 v[246:247], s[4:5], 0, v[68:69]
	v_lshl_add_u64 v[246:247], v[246:247], 0, s[26:27]
	global_load_lds_dwordx4 v[246:247], off
	v_mfma_f32_16x16x32_bf16 v[40:43], v[44:47], v[122:125], v[40:43]
	s_mov_b32 m0, s77
	v_lshl_add_u64 v[246:247], s[4:5], 0, v[76:77]
	v_lshl_add_u64 v[246:247], v[246:247], 0, s[34:35]
	global_load_lds_dwordx4 v[246:247], off
	v_mfma_f32_16x16x32_bf16 v[44:47], v[44:47], v[130:133], v[48:51]
	s_mov_b32 m0, s78
	v_lshl_add_u64 v[246:247], s[4:5], 0, v[70:71]
	v_lshl_add_u64 v[246:247], v[246:247], 0, s[26:27]
	global_load_lds_dwordx4 v[246:247], off
	v_mfma_f32_16x16x32_bf16 v[48:51], v[106:109], v[114:117], v[110:113]
	s_mov_b32 m0, s79
	v_lshl_add_u64 v[246:247], s[4:5], 0, v[78:79]
	v_lshl_add_u64 v[246:247], v[246:247], 0, s[34:35]
	global_load_lds_dwordx4 v[246:247], off
	v_mfma_f32_16x16x32_bf16 v[52:55], v[106:109], v[118:121], v[52:55]
	v_mfma_f32_16x16x32_bf16 v[56:59], v[106:109], v[122:125], v[56:59]
	v_mfma_f32_16x16x32_bf16 v[60:63], v[106:109], v[130:133], v[60:63]
	s_branch .LBB0_878
.Lge3_last0:
	v_mfma_f32_16x16x32_bf16 v[20:23], v[28:31], v[118:121], v[20:23]
	v_mfma_f32_16x16x32_bf16 v[24:27], v[28:31], v[122:125], v[24:27]
	v_mfma_f32_16x16x32_bf16 v[28:31], v[28:31], v[130:133], v[32:35]
	s_waitcnt lgkmcnt(0)
	v_mfma_f32_16x16x32_bf16 v[32:35], v[44:47], v[114:117], v[140:143]
	v_mfma_f32_16x16x32_bf16 v[36:39], v[44:47], v[118:121], v[36:39]
	v_mfma_f32_16x16x32_bf16 v[40:43], v[44:47], v[122:125], v[40:43]
	v_mfma_f32_16x16x32_bf16 v[44:47], v[44:47], v[130:133], v[48:51]
	v_mfma_f32_16x16x32_bf16 v[48:51], v[106:109], v[114:117], v[110:113]
	v_mfma_f32_16x16x32_bf16 v[52:55], v[106:109], v[118:121], v[52:55]
	v_mfma_f32_16x16x32_bf16 v[56:59], v[106:109], v[122:125], v[56:59]
	v_mfma_f32_16x16x32_bf16 v[60:63], v[106:109], v[130:133], v[60:63]
	s_branch .LBB0_878

; #define GBAR() do { asm volatile("s_waitcnt vmcnt(0) lgkmcnt(0)" ::: "memory"); __builtin_amdgcn_s_barrier(); } while (0)
; template <int EPI, bool GUARD>
; DEVI void gemm_tile(const Params& p, const bf16_t* __restrict__ A, int lda, const bf16_t* __restrict__ Bt, int ldb, int K,
;                           int row_base, int row_lo, int row_hi, int tile_n, int layer, int which, char* lds) {
;     ...
;   const int swz = c16 >> 1;
;   int koff[2];
; #pragma unroll
;   for (int ks = 0; ks < 2; ++ks) koff[ks] = ((ks * 4 + q4) ^ swz) << 4;
;   const int arow = (wr * 64 + c16) * 128, brow = 16384 + (wc * 64 + c16) * 128;
;     ...
;   GISSUE(0, 0); GBAR();
;   for (int k0 = 0; k0 < K; k0 += 128) {
;     GISSUE(k0 + 64, 1);
;     KSTEPS(0);
;     GBAR();
;     if (k0 + 128 < K) GISSUE(k0 + 128, 0);
;     KSTEPS(1);
;     GBAR();
;   }
.LBB0_959:
	ds_read_b128 v[82:85], v64 offset:32768
	ds_read_b128 v[86:89], v103 offset:49152
	ds_read_b128 v[90:93], v64 offset:34816
	ds_read_b128 v[94:97], v103 offset:51200
	ds_read_b128 v[106:109], v103 offset:53248
	ds_read_b128 v[110:113], v103 offset:55296
	s_addk_i32 s69, 0x80
	s_waitcnt lgkmcnt(0)
	v_mfma_f32_16x16x32_bf16 v[0:3], v[82:85], v[86:89], v[0:3]
	s_add_u32 s34, s34, 0x100
	s_addc_u32 s35, s35, 0
	s_and_b64 vcc, exec, s[44:45]
	v_mfma_f32_16x16x32_bf16 v[4:7], v[82:85], v[94:97], v[4:7]
	v_mfma_f32_16x16x32_bf16 v[8:11], v[82:85], v[106:109], v[8:11]
	v_mfma_f32_16x16x32_bf16 v[82:85], v[82:85], v[110:113], v[12:15]
	v_mfma_f32_16x16x32_bf16 v[16:19], v[90:93], v[86:89], v[16:19]
	v_mfma_f32_16x16x32_bf16 v[20:23], v[90:93], v[94:97], v[20:23]
	v_mfma_f32_16x16x32_bf16 v[24:27], v[90:93], v[106:109], v[24:27]
	v_mfma_f32_16x16x32_bf16 v[28:31], v[90:93], v[110:113], v[28:31]
	ds_read_b128 v[12:15], v64 offset:36864
	ds_read_b128 v[90:93], v64 offset:38912
	s_waitcnt lgkmcnt(0)
	v_mfma_f32_16x16x32_bf16 v[114:117], v[12:15], v[94:97], v[36:39]
	v_mfma_f32_16x16x32_bf16 v[52:55], v[90:93], v[94:97], v[52:55]
	ds_read_b128 v[94:97], v104 offset:32768
	v_mfma_f32_16x16x32_bf16 v[32:35], v[12:15], v[86:89], v[32:35]
	v_mfma_f32_16x16x32_bf16 v[40:43], v[12:15], v[106:109], v[40:43]
	v_mfma_f32_16x16x32_bf16 v[44:47], v[12:15], v[110:113], v[44:47]
	v_mfma_f32_16x16x32_bf16 v[86:89], v[90:93], v[86:89], v[48:51]
	v_mfma_f32_16x16x32_bf16 v[56:59], v[90:93], v[106:109], v[56:59]
	v_mfma_f32_16x16x32_bf16 v[60:63], v[90:93], v[110:113], v[60:63]
	ds_read_b128 v[90:93], v105 offset:49152
	ds_read_b128 v[106:109], v104 offset:34816
	ds_read_b128 v[110:113], v105 offset:51200
	ds_read_b128 v[118:121], v105 offset:53248
	ds_read_b128 v[128:131], v105 offset:55296
	s_waitcnt lgkmcnt(0)
	v_mfma_f32_16x16x32_bf16 v[48:51], v[94:97], v[90:93], v[0:3]
	v_mfma_f32_16x16x32_bf16 v[36:39], v[94:97], v[110:113], v[4:7]
	v_mfma_f32_16x16x32_bf16 v[12:15], v[94:97], v[118:121], v[8:11]
	v_mfma_f32_16x16x32_bf16 v[8:11], v[94:97], v[128:131], v[82:85]
	s_nop 2
	ds_read_b128 v[82:85], v104 offset:36864
	ds_read_b128 v[94:97], v104 offset:38912
	s_waitcnt vmcnt(0) lgkmcnt(0)
	s_barrier
	s_cbranch_vccnz .Lge4_exit1
	v_mfma_f32_16x16x32_bf16 v[4:7], v[106:109], v[90:93], v[16:19]
	s_add_i32 m0, s59, 0x8000
	v_lshl_add_u64 v[246:247], s[34:35], 0, v[66:67]
	v_lshl_add_u64 v[246:247], v[246:247], 0, s[4:5]
	global_load_lds_dwordx4 v[246:247], off
	v_mfma_f32_16x16x32_bf16 v[0:3], v[106:109], v[110:113], v[20:23]
	s_add_i32 m0, s59, 0xc000
	v_lshl_add_u64 v[246:247], s[34:35], 0, v[74:75]
	v_lshl_add_u64 v[246:247], v[246:247], 0, s[16:17]
	global_load_lds_dwordx4 v[246:247], off
	v_mfma_f32_16x16x32_bf16 v[16:19], v[106:109], v[118:121], v[24:27]
	s_add_i32 m0, s59, 0x8400
	v_lshl_add_u64 v[246:247], s[34:35], 0, v[68:69]
	v_lshl_add_u64 v[246:247], v[246:247], 0, s[4:5]
	global_load_lds_dwordx4 v[246:247], off
	v_mfma_f32_16x16x32_bf16 v[24:27], v[106:109], v[128:131], v[28:31]
	s_add_i32 m0, s59, 0xc400
	v_lshl_add_u64 v[246:247], s[34:35], 0, v[76:77]
	v_lshl_add_u64 v[246:247], v[246:247], 0, s[16:17]
	global_load_lds_dwordx4 v[246:247], off
	s_waitcnt lgkmcnt(0)
	v_mfma_f32_16x16x32_bf16 v[20:23], v[82:85], v[90:93], v[32:35]
	s_add_i32 m0, s59, 0x8800
	v_lshl_add_u64 v[246:247], s[34:35], 0, v[70:71]
	v_lshl_add_u64 v[246:247], v[246:247], 0, s[4:5]
	global_load_lds_dwordx4 v[246:247], off
	v_mfma_f32_16x16x32_bf16 v[28:31], v[82:85], v[110:113], v[114:117]
	s_add_i32 m0, s59, 0xc800
	v_lshl_add_u64 v[246:247], s[34:35], 0, v[78:79]
	v_lshl_add_u64 v[246:247], v[246:247], 0, s[16:17]
	global_load_lds_dwordx4 v[246:247], off
	v_mfma_f32_16x16x32_bf16 v[32:35], v[82:85], v[118:121], v[40:43]
	s_add_i32 m0, s65, 0x8000
	v_lshl_add_u64 v[246:247], s[34:35], 0, v[72:73]
	v_lshl_add_u64 v[246:247], v[246:247], 0, s[4:5]
	global_load_lds_dwordx4 v[246:247], off
	v_mfma_f32_16x16x32_bf16 v[44:47], v[82:85], v[128:131], v[44:47]
	s_add_i32 m0, s65, 0xc000
	v_lshl_add_u64 v[246:247], s[34:35], 0, v[80:81]
	v_lshl_add_u64 v[246:247], v[246:247], 0, s[16:17]
	global_load_lds_dwordx4 v[246:247], off
	v_mfma_f32_16x16x32_bf16 v[40:43], v[94:97], v[90:93], v[86:89]
	v_mfma_f32_16x16x32_bf16 v[52:55], v[94:97], v[110:113], v[52:55]
	v_mfma_f32_16x16x32_bf16 v[56:59], v[94:97], v[118:121], v[56:59]
	v_mfma_f32_16x16x32_bf16 v[60:63], v[94:97], v[128:131], v[60:63]
	s_cmpk_gt_u32 s69, 0x27f
	s_branch .Lge4_k0
.Lge4_exit1:
	v_mfma_f32_16x16x32_bf16 v[4:7], v[106:109], v[90:93], v[16:19]
	v_mfma_f32_16x16x32_bf16 v[0:3], v[106:109], v[110:113], v[20:23]
	v_mfma_f32_16x16x32_bf16 v[16:19], v[106:109], v[118:121], v[24:27]
	v_mfma_f32_16x16x32_bf16 v[24:27], v[106:109], v[128:131], v[28:31]
	s_waitcnt lgkmcnt(0)
	v_mfma_f32_16x16x32_bf16 v[20:23], v[82:85], v[90:93], v[32:35]
	v_mfma_f32_16x16x32_bf16 v[28:31], v[82:85], v[110:113], v[114:117]
	v_mfma_f32_16x16x32_bf16 v[32:35], v[82:85], v[118:121], v[40:43]
	v_mfma_f32_16x16x32_bf16 v[44:47], v[82:85], v[128:131], v[44:47]
	v_mfma_f32_16x16x32_bf16 v[40:43], v[94:97], v[90:93], v[86:89]
	v_mfma_f32_16x16x32_bf16 v[52:55], v[94:97], v[110:113], v[52:55]
	v_mfma_f32_16x16x32_bf16 v[56:59], v[94:97], v[118:121], v[56:59]
	v_mfma_f32_16x16x32_bf16 v[60:63], v[94:97], v[128:131], v[60:63]
	s_branch .LBB0_962

; #define GBAR() do { asm volatile("s_waitcnt vmcnt(0) lgkmcnt(0)" ::: "memory"); __builtin_amdgcn_s_barrier(); } while (0)
; template <int EPI, bool GUARD>
; DEVI void gemm_tile(const Params& p, const bf16_t* __restrict__ A, int lda, const bf16_t* __restrict__ Bt, int ldb, int K,
;                           int row_base, int row_lo, int row_hi, int tile_n, int layer, int which, char* lds) {
;     ...
;   const int swz = c16 >> 1;
;   int koff[2];
; #pragma unroll
;   for (int ks = 0; ks < 2; ++ks) koff[ks] = ((ks * 4 + q4) ^ swz) << 4;
;   const int arow = (wr * 64 + c16) * 128, brow = 16384 + (wc * 64 + c16) * 128;
;     ...
;   GISSUE(0, 0); GBAR();
;   for (int k0 = 0; k0 < K; k0 += 128) {
;     GISSUE(k0 + 64, 1);
;     KSTEPS(0);
;     GBAR();
;     if (k0 + 128 < K) GISSUE(k0 + 128, 0);
;     KSTEPS(1);
;     GBAR();
;   }
.Lge4_k0:
	ds_read_b128 v[106:109], v64
	ds_read_b128 v[110:113], v103 offset:16384
	ds_read_b128 v[114:117], v64 offset:2048
	ds_read_b128 v[118:121], v103 offset:18432
	ds_read_b128 v[128:131], v103 offset:20480
	ds_read_b128 v[136:139], v103 offset:22528
	s_waitcnt lgkmcnt(0)
	v_mfma_f32_16x16x32_bf16 v[140:143], v[114:117], v[110:113], v[4:7]
	s_cselect_b64 s[44:45], -1, 0
	s_and_b64 vcc, exec, s[44:45]
	v_mfma_f32_16x16x32_bf16 v[144:147], v[114:117], v[118:121], v[0:3]
	s_nop 2
	ds_read_b128 v[0:3], v64 offset:4096
	ds_read_b128 v[4:7], v64 offset:6144
	v_mfma_f32_16x16x32_bf16 v[148:151], v[114:117], v[128:131], v[16:19]
	s_nop 2
	ds_read_b128 v[16:19], v104
	v_mfma_f32_16x16x32_bf16 v[48:51], v[106:109], v[110:113], v[48:51]
	v_mfma_f32_16x16x32_bf16 v[36:39], v[106:109], v[118:121], v[36:39]
	v_mfma_f32_16x16x32_bf16 v[12:15], v[106:109], v[128:131], v[12:15]
	v_mfma_f32_16x16x32_bf16 v[106:109], v[106:109], v[136:139], v[8:11]
	v_mfma_f32_16x16x32_bf16 v[114:117], v[114:117], v[136:139], v[24:27]
	s_waitcnt lgkmcnt(0)
	v_mfma_f32_16x16x32_bf16 v[156:159], v[0:3], v[118:121], v[28:31]
	v_mfma_f32_16x16x32_bf16 v[160:163], v[0:3], v[128:131], v[32:35]
	v_mfma_f32_16x16x32_bf16 v[44:47], v[0:3], v[136:139], v[44:47]
	v_mfma_f32_16x16x32_bf16 v[52:55], v[4:7], v[118:121], v[52:55]
	v_mfma_f32_16x16x32_bf16 v[56:59], v[4:7], v[128:131], v[56:59]
	ds_read_b128 v[118:121], v105 offset:16384
	ds_read_b128 v[28:31], v104 offset:2048
	ds_read_b128 v[128:131], v105 offset:18432
	v_mfma_f32_16x16x32_bf16 v[60:63], v[4:7], v[136:139], v[60:63]
	ds_read_b128 v[136:139], v105 offset:20480
	ds_read_b128 v[166:169], v105 offset:22528
	v_mfma_f32_16x16x32_bf16 v[152:155], v[0:3], v[110:113], v[20:23]
	s_waitcnt lgkmcnt(0)
	v_mfma_f32_16x16x32_bf16 v[0:3], v[16:19], v[118:121], v[48:51]
	v_mfma_f32_16x16x32_bf16 v[8:11], v[16:19], v[136:139], v[12:15]
	v_mfma_f32_16x16x32_bf16 v[12:15], v[16:19], v[166:169], v[106:109]
	s_nop 0
	ds_read_b128 v[48:51], v104 offset:4096
	s_nop 0
	ds_read_b128 v[106:109], v104 offset:6144
	s_waitcnt vmcnt(0) lgkmcnt(0)
	s_barrier
	s_cbranch_vccnz .Lge4_last0
	v_mfma_f32_16x16x32_bf16 v[110:113], v[4:7], v[110:113], v[40:43]
	s_mov_b32 m0, s59
	v_lshl_add_u64 v[246:247], s[34:35], 0, v[66:67]
	v_lshl_add_u64 v[246:247], v[246:247], 0, s[18:19]
	global_load_lds_dwordx4 v[246:247], off
	v_mfma_f32_16x16x32_bf16 v[4:7], v[16:19], v[128:131], v[36:39]
	s_mov_b32 m0, s60
	v_lshl_add_u64 v[246:247], s[34:35], 0, v[74:75]
	v_lshl_add_u64 v[246:247], v[246:247], 0, s[26:27]
	global_load_lds_dwordx4 v[246:247], off
	v_mfma_f32_16x16x32_bf16 v[16:19], v[28:31], v[118:121], v[140:143]
	s_mov_b32 m0, s61
	v_lshl_add_u64 v[246:247], s[34:35], 0, v[68:69]
	v_lshl_add_u64 v[246:247], v[246:247], 0, s[18:19]
	global_load_lds_dwordx4 v[246:247], off
	v_mfma_f32_16x16x32_bf16 v[20:23], v[28:31], v[128:131], v[144:147]
	s_mov_b32 m0, s62
	v_lshl_add_u64 v[246:247], s[34:35], 0, v[76:77]
	v_lshl_add_u64 v[246:247], v[246:247], 0, s[26:27]
	global_load_lds_dwordx4 v[246:247], off
	v_mfma_f32_16x16x32_bf16 v[24:27], v[28:31], v[136:139], v[148:151]
	s_mov_b32 m0, s63
	v_lshl_add_u64 v[246:247], s[34:35], 0, v[70:71]
	v_lshl_add_u64 v[246:247], v[246:247], 0, s[18:19]
	global_load_lds_dwordx4 v[246:247], off
	v_mfma_f32_16x16x32_bf16 v[28:31], v[28:31], v[166:169], v[114:117]
	s_mov_b32 m0, s64
	v_lshl_add_u64 v[246:247], s[34:35], 0, v[78:79]
	v_lshl_add_u64 v[246:247], v[246:247], 0, s[26:27]
	global_load_lds_dwordx4 v[246:247], off
	s_waitcnt lgkmcnt(0)
	v_mfma_f32_16x16x32_bf16 v[32:35], v[48:51], v[118:121], v[152:155]
	s_mov_b32 m0, s65
	v_lshl_add_u64 v[246:247], s[34:35], 0, v[72:73]
	v_lshl_add_u64 v[246:247], v[246:247], 0, s[18:19]
	global_load_lds_dwordx4 v[246:247], off
	v_mfma_f32_16x16x32_bf16 v[36:39], v[48:51], v[128:131], v[156:159]
	s_mov_b32 m0, s68
	v_lshl_add_u64 v[246:247], s[34:35], 0, v[80:81]
	v_lshl_add_u64 v[246:247], v[246:247], 0, s[26:27]
	global_load_lds_dwordx4 v[246:247], off
	v_mfma_f32_16x16x32_bf16 v[40:43], v[48:51], v[136:139], v[160:163]
	v_mfma_f32_16x16x32_bf16 v[44:47], v[48:51], v[166:169], v[44:47]
	v_mfma_f32_16x16x32_bf16 v[48:51], v[106:109], v[118:121], v[110:113]
	v_mfma_f32_16x16x32_bf16 v[52:55], v[106:109], v[128:131], v[52:55]
	v_mfma_f32_16x16x32_bf16 v[56:59], v[106:109], v[136:139], v[56:59]
	v_mfma_f32_16x16x32_bf16 v[60:63], v[106:109], v[166:169], v[60:63]
	s_branch .LBB0_959
.Lge4_last0:
	v_mfma_f32_16x16x32_bf16 v[110:113], v[4:7], v[110:113], v[40:43]
	v_mfma_f32_16x16x32_bf16 v[4:7], v[16:19], v[128:131], v[36:39]
	v_mfma_f32_16x16x32_bf16 v[16:19], v[28:31], v[118:121], v[140:143]
	v_mfma_f32_16x16x32_bf16 v[20:23], v[28:31], v[128:131], v[144:147]
	v_mfma_f32_16x16x32_bf16 v[24:27], v[28:31], v[136:139], v[148:151]
	v_mfma_f32_16x16x32_bf16 v[28:31], v[28:31], v[166:169], v[114:117]
	s_waitcnt lgkmcnt(0)
	v_mfma_f32_16x16x32_bf16 v[32:35], v[48:51], v[118:121], v[152:155]
	v_mfma_f32_16x16x32_bf16 v[36:39], v[48:51], v[128:131], v[156:159]
	v_mfma_f32_16x16x32_bf16 v[40:43], v[48:51], v[136:139], v[160:163]
	v_mfma_f32_16x16x32_bf16 v[44:47], v[48:51], v[166:169], v[44:47]
	v_mfma_f32_16x16x32_bf16 v[48:51], v[106:109], v[118:121], v[110:113]
	v_mfma_f32_16x16x32_bf16 v[52:55], v[106:109], v[128:131], v[52:55]
	v_mfma_f32_16x16x32_bf16 v[56:59], v[106:109], v[136:139], v[56:59]
	v_mfma_f32_16x16x32_bf16 v[60:63], v[106:109], v[166:169], v[60:63]
	s_branch .LBB0_959

; DEVI void partialSM(f32x16& p0, f32x16& p1, float& m_reg, float& mn, float& alpha) {
;     ...
;   for (int r = 0; r < 16; ++r) p0[r] = __builtin_amdgcn_exp2f(p0[r] - mn);
; #pragma unroll
;   for (int r = 0; r < 16; ++r) p1[r] = __builtin_amdgcn_exp2f(p1[r] - mn);
; }
; DEVI void finishSM(f32x16& p0, f32x16& p1, float alpha, float& l_reg, bf16x8& pa0, bf16x8& pa1, bf16x8& pa2, bf16x8& pa3) {
;   float ps = 0;
; #pragma unroll
;   for (int r = 0; r < 16; ++r) ps += p0[r];
; #pragma unroll
;   for (int r = 0; r < 16; ++r) ps += p1[r];
;   { auto rr = __builtin_amdgcn_permlane32_swap(__float_as_uint(ps), __float_as_uint(ps), false, false);
;     ps = __uint_as_float(rr[0]) + __uint_as_float(rr[1]); }
;   l_reg = l_reg * alpha + ps;
;     ...
;   PK4(p0, 0, pa0); PK4(p0, 8, pa1); PK4(p1, 0, pa2); PK4(p1, 8, pa3);
; template <bool FIXED>
; DEVI void attn_task(const bf16_t* __restrict__ Qb, const bf16_t* __restrict__ Kh, const bf16_t* __restrict__ Vh, bf16_t* __restrict__ Ob, char* lds, float shiftC) {
;     ...
;     for (int d0 = 0; d0 < 12; ++d0) {
;       const bf16x8 b0 = *(const bf16x8*)(Kr0 + (d0 >> 2) * 128 + kx[d0 & 3]);
;       const bf16x8 b1 = *(const bf16x8*)(Kr0 + 32 * 384 + (d0 >> 2) * 128 + kx[d0 & 3]);
;       p0 = __builtin_amdgcn_mfma_f32_32x32x16_bf16(b0, qr[d0], p0, 0, 0, 0);
;       p1 = __builtin_amdgcn_mfma_f32_32x32x16_bf16(b1, qr[d0], p1, 0, 0, 0);
;     }
;     ABAR();
;     if (j + 1 < NT) KISSUE((j + 1) * 64);
;     float mn, alpha = 1.f;
;     if constexpr (FIXED) {
; #pragma unroll
;       for (int r = 0; r < 16; ++r) p0[r] = __builtin_amdgcn_exp2f(p0[r]);
; #pragma unroll
;       for (int r = 0; r < 16; ++r) p1[r] = __builtin_amdgcn_exp2f(p1[r]);
;     } else partialSM(p0, p1, m_reg, mn, alpha);
;     if (!FIXED && __any(alpha < 1.f)) {
;       if (hi == 0) al_l[r32] = alpha;
;       asm volatile("s_waitcnt lgkmcnt(0)" ::: "memory");
; #pragma unroll
;       for (int r = 0; r < 16; ++r) { const float a = al_l[crow(r, hi)];
; #pragma unroll
;         for (int d = 0; d < 4; ++d) o[d][r] *= a; }
;     }
;     bf16x8 pa0, pa1, pa2, pa3;
;     finishSM(p0, p1, alpha, l_reg, pa0, pa1, pa2, pa3);
;     pv_one<0>(o[0], vb0, pa0, pa1, pa2, pa3); pv_one<1>(o[1], vb0, pa0, pa1, pa2, pa3);
;     pv_one<2>(o[2], vb0, pa0, pa1, pa2, pa3); pv_one<3>(o[3], vb0, pa0, pa1, pa2, pa3);
;     ABAR();
;     if (j + 1 < NT) VISSUE((j + 1) * 64);
.LBB0_1046:
	s_mov_b32 m0, s26
	s_waitcnt lgkmcnt(8)
	v_mfma_f32_32x32x16_bf16 v[66:81], v[186:189], v[142:145], 0
	ds_read_b128 v[186:189], v180 offset:256
	s_waitcnt lgkmcnt(8)
	v_mfma_f32_32x32x16_bf16 v[66:81], v[190:193], v[138:141], v[66:81]
	ds_read_b128 v[190:193], v179 offset:256
	s_waitcnt lgkmcnt(8)
	v_mfma_f32_32x32x16_bf16 v[66:81], v[194:197], v[134:137], v[66:81]
	ds_read_b128 v[194:197], v178 offset:256
	s_waitcnt lgkmcnt(8)
	v_mfma_f32_32x32x16_bf16 v[66:81], v[198:201], v[126:129], v[66:81]
	ds_read_b128 v[198:201], v181 offset:12288
	s_waitcnt lgkmcnt(8)
	v_mfma_f32_32x32x16_bf16 v[66:81], v[202:205], v[130:133], v[66:81]
	ds_read_b128 v[202:205], v180 offset:12288
	s_waitcnt lgkmcnt(8)
	v_mfma_f32_32x32x16_bf16 v[66:81], v[206:209], v[118:121], v[66:81]
	ds_read_b128 v[206:209], v179 offset:12288
	s_waitcnt lgkmcnt(8)
	v_mfma_f32_32x32x16_bf16 v[66:81], v[210:213], v[122:125], v[66:81]
	ds_read_b128 v[210:213], v178 offset:12288
	s_waitcnt lgkmcnt(8)
	v_mfma_f32_32x32x16_bf16 v[66:81], v[214:217], v[110:113], v[66:81]
	ds_read_b128 v[214:217], v181 offset:12416
	s_waitcnt lgkmcnt(8)
	v_mfma_f32_32x32x16_bf16 v[66:81], v[222:225], v[114:117], v[66:81]
	ds_read_b128 v[222:225], v180 offset:12416
	s_waitcnt lgkmcnt(8)
	v_mfma_f32_32x32x16_bf16 v[66:81], v[186:189], v[106:109], v[66:81]
	ds_read_b128 v[186:189], v179 offset:12416
	s_waitcnt lgkmcnt(8)
	v_mfma_f32_32x32x16_bf16 v[66:81], v[190:193], v[102:105], v[66:81]
	ds_read_b128 v[190:193], v178 offset:12416
	s_waitcnt lgkmcnt(8)
	v_mfma_f32_32x32x16_bf16 v[66:81], v[194:197], v[98:101], v[66:81]
	ds_read_b128 v[194:197], v181 offset:12544
	s_waitcnt lgkmcnt(8)
	v_mfma_f32_32x32x16_bf16 v[82:97], v[198:201], v[142:145], 0
	ds_read_b128 v[198:201], v180 offset:12544
	s_waitcnt lgkmcnt(8)
	v_mfma_f32_32x32x16_bf16 v[82:97], v[202:205], v[138:141], v[82:97]
	ds_read_b128 v[202:205], v179 offset:12544
	s_waitcnt lgkmcnt(8)
	v_mfma_f32_32x32x16_bf16 v[82:97], v[206:209], v[134:137], v[82:97]
	ds_read_b128 v[206:209], v178 offset:12544
	s_waitcnt lgkmcnt(8)
	v_mfma_f32_32x32x16_bf16 v[82:97], v[210:213], v[126:129], v[82:97]
	v_exp_f32_e32 v66, v66
	v_exp_f32_e32 v67, v67
	v_exp_f32_e32 v68, v68
	v_exp_f32_e32 v69, v69
	s_waitcnt lgkmcnt(7)
	v_mfma_f32_32x32x16_bf16 v[82:97], v[214:217], v[130:133], v[82:97]
	v_exp_f32_e32 v70, v70
	v_add_f32_e32 v182, 0, v66
	v_exp_f32_e32 v71, v71
	v_add_f32_e32 v182, v67, v182
	s_waitcnt vmcnt(0) lgkmcnt(0)
	s_barrier
	v_mfma_f32_32x32x16_bf16 v[82:97], v[222:225], v[118:121], v[82:97]
	v_exp_f32_e32 v72, v72
	v_add_f32_e32 v182, v68, v182
	global_load_lds_dwordx4 v152, s[98:99]
	s_mov_b32 m0, s27
	v_exp_f32_e32 v73, v73
	v_add_f32_e32 v182, v69, v182
	global_load_lds_dwordx4 v154, s[98:99]
	v_mfma_f32_32x32x16_bf16 v[82:97], v[186:189], v[122:125], v[82:97]
	s_mov_b32 m0, s54
	v_exp_f32_e32 v74, v74
	v_add_f32_e32 v182, v70, v182
	global_load_lds_dwordx4 v156, s[98:99]
	s_mov_b32 m0, s55
	v_exp_f32_e32 v75, v75
	v_add_f32_e32 v182, v71, v182
	global_load_lds_dwordx4 v158, s[98:99]
	v_mfma_f32_32x32x16_bf16 v[82:97], v[190:193], v[110:113], v[82:97]
	s_mov_b32 m0, s56
	v_exp_f32_e32 v76, v76
	v_add_f32_e32 v182, v72, v182
	global_load_lds_dwordx4 v160, s[98:99]
	s_mov_b32 m0, s57
	v_exp_f32_e32 v77, v77
	v_add_f32_e32 v182, v73, v182
	global_load_lds_dwordx4 v162, s[98:99]
	s_add_u32 s98, s98, 0x6000
	s_addc_u32 s99, s99, 0
	v_mfma_f32_32x32x16_bf16 v[82:97], v[194:197], v[114:117], v[82:97]
	v_exp_f32_e32 v78, v78
	v_add_f32_e32 v182, v74, v182
	v_exp_f32_e32 v79, v79
	v_add_f32_e32 v182, v75, v182
	ds_read_b64_tr_b16 v[226:227], v176 offset:0
	ds_read_b64_tr_b16 v[228:229], v176 offset:2048
	v_mfma_f32_32x32x16_bf16 v[82:97], v[198:201], v[106:109], v[82:97]
	v_exp_f32_e32 v80, v80
	v_add_f32_e32 v182, v76, v182
	v_exp_f32_e32 v81, v81
	v_add_f32_e32 v182, v77, v182
	ds_read_b64_tr_b16 v[230:231], v176 offset:512
	ds_read_b64_tr_b16 v[232:233], v176 offset:2560
	v_mfma_f32_32x32x16_bf16 v[82:97], v[202:205], v[102:105], v[82:97]
	v_add_f32_e32 v182, v78, v182
	v_add_f32_e32 v182, v79, v182
	v_add_f32_e32 v182, v80, v182
	v_add_f32_e32 v182, v81, v182
	v_cvt_pk_bf16_f32 v66, v66, v67
	v_cvt_pk_bf16_f32 v67, v68, v69
	v_cvt_pk_bf16_f32 v68, v70, v71
	v_cvt_pk_bf16_f32 v69, v72, v73
	ds_read_b64_tr_b16 v[234:235], v176 offset:1024
	ds_read_b64_tr_b16 v[236:237], v176 offset:3072
	v_mfma_f32_32x32x16_bf16 v[82:97], v[206:209], v[98:101], v[82:97]
	v_permlane32_swap_b32_e32 v66, v68
	v_permlane32_swap_b32_e32 v67, v69
	v_cvt_pk_bf16_f32 v70, v74, v75
	v_cvt_pk_bf16_f32 v71, v76, v77
	v_cvt_pk_bf16_f32 v72, v78, v79
	v_cvt_pk_bf16_f32 v73, v80, v81
	ds_read_b64_tr_b16 v[238:239], v176 offset:1536
	ds_read_b64_tr_b16 v[240:241], v176 offset:3584
	ds_read_b64_tr_b16 v[210:211], v176 offset:4096
	ds_read_b64_tr_b16 v[212:213], v176 offset:6144
	s_waitcnt lgkmcnt(8)
	v_mfma_f32_32x32x16_bf16 v[50:65], v[66:69], v[226:229], v[50:65]
	v_permlane32_swap_b32_e32 v70, v72
	v_permlane32_swap_b32_e32 v71, v73
	v_exp_f32_e32 v82, v82
	v_exp_f32_e32 v83, v83
	v_exp_f32_e32 v84, v84
	ds_read_b64_tr_b16 v[214:215], v176 offset:4608
	ds_read_b64_tr_b16 v[216:217], v176 offset:6656
	s_waitcnt lgkmcnt(8)
	v_mfma_f32_32x32x16_bf16 v[34:49], v[66:69], v[230:233], v[34:49]
	v_exp_f32_e32 v85, v85
	v_exp_f32_e32 v86, v86
	v_add_f32_e32 v182, v82, v182
	v_exp_f32_e32 v87, v87
	v_add_f32_e32 v182, v83, v182
	ds_read_b64_tr_b16 v[218:219], v176 offset:5120
	ds_read_b64_tr_b16 v[220:221], v176 offset:7168
	s_waitcnt lgkmcnt(8)
; DEVI void finishSM(f32x16& p0, f32x16& p1, float alpha, float& l_reg, bf16x8& pa0, bf16x8& pa1, bf16x8& pa2, bf16x8& pa3) {
;   float ps = 0;
; #pragma unroll
;   for (int r = 0; r < 16; ++r) ps += p0[r];
; #pragma unroll
;   for (int r = 0; r < 16; ++r) ps += p1[r];
;   { auto rr = __builtin_amdgcn_permlane32_swap(__float_as_uint(ps), __float_as_uint(ps), false, false);
;     ps = __uint_as_float(rr[0]) + __uint_as_float(rr[1]); }
;   l_reg = l_reg * alpha + ps;
;     ...
;   PK4(p0, 0, pa0); PK4(p0, 8, pa1); PK4(p1, 0, pa2); PK4(p1, 8, pa3);
;     ...
; }
; DEVI int v_st(int k) { const int kk = (k & ~0xC) | ((k & 4) << 1) | ((k & 8) >> 1); return ((kk >> 3) * 4) * 512 + ((kk & 7) * 32) * 2; }
; DEVI int v_rd_base(int lane) { return ((lane & 3) << 3) | (((lane >> 2) & 3) << 6) | (((lane >> 4) & 1) << 5) | (((lane >> 5) & 1) << 8); }
; template <bool FIXED>
; DEVI void attn_task(const bf16_t* __restrict__ Qb, const bf16_t* __restrict__ Kh, const bf16_t* __restrict__ Vh, bf16_t* __restrict__ Ob, char* lds, float shiftC) {
;     ...
;     for (int d0 = 0; d0 < 12; ++d0) {
;       const bf16x8 b0 = *(const bf16x8*)(Kr0 + (d0 >> 2) * 128 + kx[d0 & 3]);
;       const bf16x8 b1 = *(const bf16x8*)(Kr0 + 32 * 384 + (d0 >> 2) * 128 + kx[d0 & 3]);
;       p0 = __builtin_amdgcn_mfma_f32_32x32x16_bf16(b0, qr[d0], p0, 0, 0, 0);
;       p1 = __builtin_amdgcn_mfma_f32_32x32x16_bf16(b1, qr[d0], p1, 0, 0, 0);
;     }
;     ABAR();
;     if (j + 1 < NT) KISSUE((j + 1) * 64);
;     float mn, alpha = 1.f;
;     if constexpr (FIXED) {
; #pragma unroll
;       for (int r = 0; r < 16; ++r) p0[r] = __builtin_amdgcn_exp2f(p0[r]);
; #pragma unroll
;       for (int r = 0; r < 16; ++r) p1[r] = __builtin_amdgcn_exp2f(p1[r]);
;     } else partialSM(p0, p1, m_reg, mn, alpha);
;     if (!FIXED && __any(alpha < 1.f)) {
;       if (hi == 0) al_l[r32] = alpha;
;       asm volatile("s_waitcnt lgkmcnt(0)" ::: "memory");
; #pragma unroll
;       for (int r = 0; r < 16; ++r) { const float a = al_l[crow(r, hi)];
; #pragma unroll
;         for (int d = 0; d < 4; ++d) o[d][r] *= a; }
;     }
;     bf16x8 pa0, pa1, pa2, pa3;
;     finishSM(p0, p1, alpha, l_reg, pa0, pa1, pa2, pa3);
;     pv_one<0>(o[0], vb0, pa0, pa1, pa2, pa3); pv_one<1>(o[1], vb0, pa0, pa1, pa2, pa3);
;     pv_one<2>(o[2], vb0, pa0, pa1, pa2, pa3); pv_one<3>(o[3], vb0, pa0, pa1, pa2, pa3);
;     ABAR();
;     if (j + 1 < NT) VISSUE((j + 1) * 64);
	v_mfma_f32_32x32x16_bf16 v[18:33], v[66:69], v[234:237], v[18:33]
	v_exp_f32_e32 v88, v88
	v_add_f32_e32 v182, v84, v182
	v_exp_f32_e32 v89, v89
	v_add_f32_e32 v182, v85, v182
	v_exp_f32_e32 v90, v90
	ds_read_b64_tr_b16 v[222:223], v176 offset:5632
	ds_read_b64_tr_b16 v[224:225], v176 offset:7680
	s_waitcnt lgkmcnt(8)
	v_mfma_f32_32x32x16_bf16 v[2:17], v[66:69], v[238:241], v[2:17]
	v_add_f32_e32 v182, v86, v182
	v_exp_f32_e32 v91, v91
	v_add_f32_e32 v182, v87, v182
	v_exp_f32_e32 v92, v92
	v_add_f32_e32 v182, v88, v182
	ds_read_b64_tr_b16 v[186:187], v176 offset:8192
	ds_read_b64_tr_b16 v[188:189], v176 offset:10240
	s_waitcnt lgkmcnt(8)
	v_mfma_f32_32x32x16_bf16 v[50:65], v[70:73], v[210:213], v[50:65]
	v_exp_f32_e32 v93, v93
	v_add_f32_e32 v182, v89, v182
	v_exp_f32_e32 v94, v94
	v_add_f32_e32 v182, v90, v182
	v_exp_f32_e32 v95, v95
	ds_read_b64_tr_b16 v[190:191], v176 offset:8704
	ds_read_b64_tr_b16 v[192:193], v176 offset:10752
	s_waitcnt lgkmcnt(8)
	v_mfma_f32_32x32x16_bf16 v[34:49], v[70:73], v[214:217], v[34:49]
	v_add_f32_e32 v182, v91, v182
	v_exp_f32_e32 v96, v96
	v_add_f32_e32 v182, v92, v182
	v_exp_f32_e32 v97, v97
	v_add_f32_e32 v182, v93, v182
	ds_read_b64_tr_b16 v[194:195], v176 offset:9216
	ds_read_b64_tr_b16 v[196:197], v176 offset:11264
	s_waitcnt lgkmcnt(8)
	v_mfma_f32_32x32x16_bf16 v[18:33], v[70:73], v[218:221], v[18:33]
	v_add_f32_e32 v182, v94, v182
	v_add_f32_e32 v182, v95, v182
	v_add_f32_e32 v182, v96, v182
	v_add_f32_e32 v182, v97, v182
	ds_read_b64_tr_b16 v[198:199], v176 offset:9728
	ds_read_b64_tr_b16 v[200:201], v176 offset:11776
	s_waitcnt lgkmcnt(8)
	v_mfma_f32_32x32x16_bf16 v[2:17], v[70:73], v[222:225], v[2:17]
	v_cvt_pk_bf16_f32 v74, v82, v83
	v_cvt_pk_bf16_f32 v75, v84, v85
	v_cvt_pk_bf16_f32 v76, v86, v87
	v_cvt_pk_bf16_f32 v77, v88, v89
	v_mov_b32_e32 v183, v182
	v_cvt_pk_bf16_f32 v78, v90, v91
	v_cvt_pk_bf16_f32 v79, v92, v93
	v_permlane32_swap_b32_e32 v74, v76
	v_permlane32_swap_b32_e32 v75, v77
	v_cvt_pk_bf16_f32 v80, v94, v95
	v_cvt_pk_bf16_f32 v81, v96, v97
	v_permlane32_swap_b32_e32 v182, v183
	ds_read_b64_tr_b16 v[82:83], v176 offset:12288
	ds_read_b64_tr_b16 v[84:85], v176 offset:14336
	v_add_f32_e32 v182, v182, v183
	v_add_f32_e32 v0, v0, v182
	s_waitcnt lgkmcnt(8)
	v_mfma_f32_32x32x16_bf16 v[50:65], v[74:77], v[186:189], v[50:65]
	v_permlane32_swap_b32_e32 v78, v80
	v_permlane32_swap_b32_e32 v79, v81
	ds_read_b64_tr_b16 v[86:87], v176 offset:12800
	ds_read_b64_tr_b16 v[88:89], v176 offset:14848
	s_waitcnt lgkmcnt(8)
	v_mfma_f32_32x32x16_bf16 v[34:49], v[74:77], v[190:193], v[34:49]
	ds_read_b64_tr_b16 v[90:91], v176 offset:13312
	ds_read_b64_tr_b16 v[92:93], v176 offset:15360
	s_waitcnt lgkmcnt(8)
	v_mfma_f32_32x32x16_bf16 v[18:33], v[74:77], v[194:197], v[18:33]
	ds_read_b64_tr_b16 v[94:95], v176 offset:13824
	ds_read_b64_tr_b16 v[96:97], v176 offset:15872
	s_waitcnt lgkmcnt(8)
	v_mfma_f32_32x32x16_bf16 v[2:17], v[74:77], v[198:201], v[2:17]
	s_waitcnt lgkmcnt(6)
	v_mfma_f32_32x32x16_bf16 v[50:65], v[78:81], v[82:85], v[50:65]
	s_waitcnt vmcnt(0) lgkmcnt(0)
	s_barrier
	s_mov_b32 m0, s58
	ds_read_b128 v[186:189], v181
	global_load_lds_dwordx4 v242, s[100:101]
	s_mov_b32 m0, s59
	ds_read_b128 v[190:193], v180
	global_load_lds_dwordx4 v150, s[100:101]
	v_mfma_f32_32x32x16_bf16 v[34:49], v[78:81], v[86:89], v[34:49]
	s_mov_b32 m0, s60
	ds_read_b128 v[194:197], v179
	global_load_lds_dwordx4 v243, s[100:101]
	s_mov_b32 m0, s61
	ds_read_b128 v[198:201], v178
	global_load_lds_dwordx4 v146, s[100:101]
	s_add_u32 s100, s100, 0x4000
	s_addc_u32 s101, s101, 0
	v_mfma_f32_32x32x16_bf16 v[18:33], v[78:81], v[90:93], v[18:33]
	ds_read_b128 v[202:205], v181 offset:128
	ds_read_b128 v[206:209], v180 offset:128
	ds_read_b128 v[210:213], v179 offset:128
	ds_read_b128 v[214:217], v178 offset:128
	ds_read_b128 v[222:225], v181 offset:256
	s_add_i32 s62, s62, -1
	s_cmp_lg_u32 s62, 0
	v_mfma_f32_32x32x16_bf16 v[2:17], v[78:81], v[94:97], v[2:17]
	s_cbranch_scc1 .LBB0_1046
	ds_read_b128 v[66:69], v181
	ds_read_b128 v[146:149], v181 offset:128
	ds_read_b128 v[82:85], v181 offset:12288
	ds_read_b128 v[150:153], v181 offset:256
	s_waitcnt lgkmcnt(0)
	v_mfma_f32_32x32x16_bf16 v[66:81], v[66:69], v[142:145], 0
	v_mfma_f32_32x32x16_bf16 v[82:97], v[82:85], v[142:145], 0
	ds_read_b128 v[142:145], v180
	ds_read_b128 v[154:157], v180 offset:128
	s_waitcnt lgkmcnt(0)
	v_mfma_f32_32x32x16_bf16 v[66:81], v[142:145], v[138:141], v[66:81]
	ds_read_b128 v[142:145], v180 offset:12288
	ds_read_b128 v[158:161], v180 offset:256
	s_waitcnt lgkmcnt(0)
	v_mfma_f32_32x32x16_bf16 v[82:97], v[142:145], v[138:141], v[82:97]
	ds_read_b128 v[138:141], v179
	ds_read_b128 v[142:145], v179 offset:128
	s_waitcnt lgkmcnt(0)
	v_mfma_f32_32x32x16_bf16 v[66:81], v[138:141], v[134:137], v[66:81]
	ds_read_b128 v[138:141], v179 offset:12288
	ds_read_b128 v[182:185], v179 offset:256
	s_waitcnt lgkmcnt(0)
	v_mfma_f32_32x32x16_bf16 v[82:97], v[138:141], v[134:137], v[82:97]
	ds_read_b128 v[134:137], v178
	ds_read_b128 v[138:141], v178 offset:128
	s_waitcnt lgkmcnt(0)
	v_mfma_f32_32x32x16_bf16 v[66:81], v[134:137], v[126:129], v[66:81]
	ds_read_b128 v[134:137], v178 offset:12288
	ds_read_b128 v[186:189], v178 offset:256
	v_mfma_f32_32x32x16_bf16 v[66:81], v[146:149], v[130:133], v[66:81]
	s_waitcnt lgkmcnt(0)
	v_mfma_f32_32x32x16_bf16 v[82:97], v[134:137], v[126:129], v[82:97]
	ds_read_b128 v[126:129], v181 offset:12416
	ds_read_b128 v[134:137], v181 offset:12544
	v_mfma_f32_32x32x16_bf16 v[66:81], v[154:157], v[118:121], v[66:81]
	s_waitcnt lgkmcnt(0)
	v_mfma_f32_32x32x16_bf16 v[82:97], v[126:129], v[130:133], v[82:97]
	ds_read_b128 v[126:129], v180 offset:12416
	ds_read_b128 v[130:133], v180 offset:12544
	v_mfma_f32_32x32x16_bf16 v[66:81], v[142:145], v[122:125], v[66:81]
	s_waitcnt lgkmcnt(0)
	v_mfma_f32_32x32x16_bf16 v[82:97], v[126:129], v[118:121], v[82:97]
	ds_read_b128 v[118:121], v179 offset:12416
	ds_read_b128 v[126:129], v179 offset:12544
	v_mfma_f32_32x32x16_bf16 v[66:81], v[138:141], v[110:113], v[66:81]
	s_waitcnt lgkmcnt(0)
	v_mfma_f32_32x32x16_bf16 v[82:97], v[118:121], v[122:125], v[82:97]
	ds_read_b128 v[118:121], v178 offset:12416
	ds_read_b128 v[122:125], v178 offset:12544
	s_waitcnt vmcnt(0) lgkmcnt(0)
	s_barrier
; DEVI void finishSM(f32x16& p0, f32x16& p1, float alpha, float& l_reg, bf16x8& pa0, bf16x8& pa1, bf16x8& pa2, bf16x8& pa3) {
;   float ps = 0;
; #pragma unroll
;   for (int r = 0; r < 16; ++r) ps += p0[r];
; #pragma unroll
;   for (int r = 0; r < 16; ++r) ps += p1[r];
;   { auto rr = __builtin_amdgcn_permlane32_swap(__float_as_uint(ps), __float_as_uint(ps), false, false);
;     ps = __uint_as_float(rr[0]) + __uint_as_float(rr[1]); }
;   l_reg = l_reg * alpha + ps;
;     ...
;   PK4(p0, 0, pa0); PK4(p0, 8, pa1); PK4(p1, 0, pa2); PK4(p1, 8, pa3);
;     ...
; }
; DEVI int v_st(int k) { const int kk = (k & ~0xC) | ((k & 4) << 1) | ((k & 8) >> 1); return ((kk >> 3) * 4) * 512 + ((kk & 7) * 32) * 2; }
; DEVI int v_rd_base(int lane) { return ((lane & 3) << 3) | (((lane >> 2) & 3) << 6) | (((lane >> 4) & 1) << 5) | (((lane >> 5) & 1) << 8); }
; template <bool FIXED>
; DEVI void attn_task(const bf16_t* __restrict__ Qb, const bf16_t* __restrict__ Kh, const bf16_t* __restrict__ Vh, bf16_t* __restrict__ Ob, char* lds, float shiftC) {
;     ...
;     for (int d0 = 0; d0 < 12; ++d0) {
;       const bf16x8 b0 = *(const bf16x8*)(Kr0 + (d0 >> 2) * 128 + kx[d0 & 3]);
;       const bf16x8 b1 = *(const bf16x8*)(Kr0 + 32 * 384 + (d0 >> 2) * 128 + kx[d0 & 3]);
;       p0 = __builtin_amdgcn_mfma_f32_32x32x16_bf16(b0, qr[d0], p0, 0, 0, 0);
;       p1 = __builtin_amdgcn_mfma_f32_32x32x16_bf16(b1, qr[d0], p1, 0, 0, 0);
;     }
;     ABAR();
;     if (j + 1 < NT) KISSUE((j + 1) * 64);
;     float mn, alpha = 1.f;
;     if constexpr (FIXED) {
; #pragma unroll
;       for (int r = 0; r < 16; ++r) p0[r] = __builtin_amdgcn_exp2f(p0[r]);
; #pragma unroll
;       for (int r = 0; r < 16; ++r) p1[r] = __builtin_amdgcn_exp2f(p1[r]);
;     } else partialSM(p0, p1, m_reg, mn, alpha);
;     if (!FIXED && __any(alpha < 1.f)) {
;       if (hi == 0) al_l[r32] = alpha;
;       asm volatile("s_waitcnt lgkmcnt(0)" ::: "memory");
; #pragma unroll
;       for (int r = 0; r < 16; ++r) { const float a = al_l[crow(r, hi)];
; #pragma unroll
;         for (int d = 0; d < 4; ++d) o[d][r] *= a; }
;     }
;     bf16x8 pa0, pa1, pa2, pa3;
;     finishSM(p0, p1, alpha, l_reg, pa0, pa1, pa2, pa3);
;     pv_one<0>(o[0], vb0, pa0, pa1, pa2, pa3); pv_one<1>(o[1], vb0, pa0, pa1, pa2, pa3);
;     pv_one<2>(o[2], vb0, pa0, pa1, pa2, pa3); pv_one<3>(o[3], vb0, pa0, pa1, pa2, pa3);
;     ABAR();
;     if (j + 1 < NT) VISSUE((j + 1) * 64);
	v_mfma_f32_32x32x16_bf16 v[66:81], v[150:153], v[114:117], v[66:81]
	s_waitcnt lgkmcnt(0)
	v_mfma_f32_32x32x16_bf16 v[82:97], v[118:121], v[110:113], v[82:97]
	v_and_b32_e32 v110, 0x3fffffc0, v177
	v_lshl_add_u32 v110, v110, 2, 0
	v_mfma_f32_32x32x16_bf16 v[66:81], v[158:161], v[106:109], v[66:81]
	v_mfma_f32_32x32x16_bf16 v[82:97], v[134:137], v[114:117], v[82:97]
	v_mfma_f32_32x32x16_bf16 v[66:81], v[182:185], v[102:105], v[66:81]
	v_mfma_f32_32x32x16_bf16 v[66:81], v[186:189], v[98:101], v[66:81]
	v_mfma_f32_32x32x16_bf16 v[82:97], v[130:133], v[106:109], v[82:97]
	s_nop 10
	v_exp_f32_e32 v111, v66
	v_exp_f32_e32 v112, v67
	v_exp_f32_e32 v106, v68
	v_exp_f32_e32 v69, v69
	v_exp_f32_e32 v70, v70
	v_add_f32_e32 v66, 0, v111
	v_exp_f32_e32 v71, v71
	v_mfma_f32_32x32x16_bf16 v[82:97], v[126:129], v[102:105], v[82:97]
	v_add_f32_e32 v66, v112, v66
	v_exp_f32_e32 v72, v72
	v_add_f32_e32 v66, v106, v66
	v_exp_f32_e32 v73, v73
	v_add_f32_e32 v66, v69, v66
	v_exp_f32_e32 v74, v74
	v_add_f32_e32 v66, v70, v66
	v_mfma_f32_32x32x16_bf16 v[82:97], v[122:125], v[98:101], v[82:97]
	v_exp_f32_e32 v75, v75
	v_add_f32_e32 v66, v71, v66
	v_exp_f32_e32 v76, v76
	v_add_f32_e32 v66, v72, v66
	v_exp_f32_e32 v77, v77
	v_add_f32_e32 v66, v73, v66
	v_exp_f32_e32 v78, v78
	v_add_f32_e32 v66, v74, v66
	v_exp_f32_e32 v79, v79
	v_add_f32_e32 v66, v75, v66
	v_exp_f32_e32 v80, v80
	v_add_f32_e32 v66, v76, v66
	v_exp_f32_e32 v81, v81
	v_add_f32_e32 v66, v77, v66
	v_exp_f32_e32 v82, v82
	v_add_f32_e32 v66, v78, v66
	v_exp_f32_e32 v83, v83
	v_add_f32_e32 v66, v79, v66
	v_exp_f32_e32 v84, v84
	v_add_f32_e32 v66, v80, v66
	v_exp_f32_e32 v85, v85
	v_add_f32_e32 v66, v81, v66
	v_exp_f32_e32 v86, v86
	v_add_f32_e32 v66, v82, v66
	v_exp_f32_e32 v87, v87
	v_add_f32_e32 v66, v83, v66
	v_exp_f32_e32 v88, v88
	v_add_f32_e32 v66, v84, v66
	v_exp_f32_e32 v89, v89
	v_add_f32_e32 v66, v85, v66
	v_exp_f32_e32 v90, v90
	v_add_f32_e32 v66, v86, v66
	v_exp_f32_e32 v91, v91
	v_add_f32_e32 v66, v87, v66
	v_exp_f32_e32 v92, v92
	v_add_f32_e32 v66, v88, v66
	v_exp_f32_e32 v93, v93
	v_add_f32_e32 v66, v89, v66
	v_exp_f32_e32 v94, v94
	v_add_f32_e32 v66, v90, v66
	v_exp_f32_e32 v95, v95
	v_add_f32_e32 v66, v91, v66
	v_cvt_pk_bf16_f32 v70, v70, v71
	v_cvt_pk_bf16_f32 v71, v72, v73
	v_cvt_pk_bf16_f32 v73, v76, v77
	v_cvt_pk_bf16_f32 v77, v84, v85
	ds_read_b64_tr_b16 v[84:85], v176 offset:0
	v_exp_f32_e32 v96, v96
	v_add_f32_e32 v66, v92, v66
	v_cvt_pk_bf16_f32 v72, v74, v75
	v_cvt_pk_bf16_f32 v74, v78, v79
	v_cvt_pk_bf16_f32 v78, v86, v87
	ds_read_b64_tr_b16 v[86:87], v176 offset:0x800
	v_exp_f32_e32 v97, v97
	v_add_f32_e32 v66, v93, v66
	v_cvt_pk_bf16_f32 v79, v88, v89
	ds_read_b64_tr_b16 v[88:89], v176 offset:0x1000
	v_add_f32_e32 v66, v94, v66
	v_cvt_pk_bf16_f32 v75, v80, v81
	v_cvt_pk_bf16_f32 v80, v90, v91
	ds_read_b64_tr_b16 v[90:91], v176 offset:0x1800
	v_add_f32_e32 v66, v95, v66
	v_cvt_pk_bf16_f32 v81, v92, v93
	ds_read_b64_tr_b16 v[92:93], v176 offset:0x2000
	v_add_f32_e32 v66, v96, v66
	v_cvt_pk_bf16_f32 v76, v82, v83
	v_cvt_pk_bf16_f32 v82, v94, v95
	ds_read_b64_tr_b16 v[94:95], v176 offset:0x2800
	v_add_f32_e32 v66, v97, v66
	v_cvt_pk_bf16_f32 v83, v96, v97
	ds_read_b64_tr_b16 v[96:97], v176 offset:0x3000
	ds_read_b64_tr_b16 v[98:99], v176 offset:0x3800
	s_waitcnt lgkmcnt(0)
	v_mov_b32_e32 v67, v66
	s_nop 1
	v_permlane32_swap_b32_e32 v66, v67
	v_cvt_pk_bf16_f32 v68, v111, v112
	v_cvt_pk_bf16_f32 v69, v106, v69
	v_permlane32_swap_b32_e32 v72, v74
	v_permlane32_swap_b32_e32 v68, v70
	v_permlane32_swap_b32_e32 v69, v71
	v_permlane32_swap_b32_e32 v73, v75
	v_permlane32_swap_b32_e32 v76, v78
	v_permlane32_swap_b32_e32 v77, v79
	v_permlane32_swap_b32_e32 v80, v82
	v_permlane32_swap_b32_e32 v81, v83
	v_mfma_f32_32x32x16_bf16 v[50:65], v[68:71], v[84:87], v[50:65]
	ds_read_b64_tr_b16 v[84:85], v176 offset:0x200
	ds_read_b64_tr_b16 v[86:87], v176 offset:0xa00
	v_mfma_f32_32x32x16_bf16 v[50:65], v[72:75], v[88:91], v[50:65]
	ds_read_b64_tr_b16 v[88:89], v176 offset:0x1200
	ds_read_b64_tr_b16 v[90:91], v176 offset:0x1a00
	v_mfma_f32_32x32x16_bf16 v[50:65], v[76:79], v[92:95], v[50:65]
	ds_read_b64_tr_b16 v[92:93], v176 offset:0x2200
	ds_read_b64_tr_b16 v[94:95], v176 offset:0x2a00
	ds_read_b64_tr_b16 v[100:101], v176 offset:0x3200
	ds_read_b64_tr_b16 v[102:103], v176 offset:0x3a00
	s_waitcnt lgkmcnt(0)
	v_mfma_f32_32x32x16_bf16 v[50:65], v[80:83], v[96:99], v[50:65]
	v_mfma_f32_32x32x16_bf16 v[34:49], v[68:71], v[84:87], v[34:49]
	ds_read_b64_tr_b16 v[84:85], v176 offset:0x400
	ds_read_b64_tr_b16 v[86:87], v176 offset:0xc00
	v_mfma_f32_32x32x16_bf16 v[34:49], v[72:75], v[88:91], v[34:49]
	ds_read_b64_tr_b16 v[88:89], v176 offset:0x1400
	ds_read_b64_tr_b16 v[90:91], v176 offset:0x1c00
	v_mfma_f32_32x32x16_bf16 v[34:49], v[76:79], v[92:95], v[34:49]
	ds_read_b64_tr_b16 v[92:93], v176 offset:0x2400
	ds_read_b64_tr_b16 v[94:95], v176 offset:0x2c00
	ds_read_b64_tr_b16 v[96:97], v176 offset:0x3400
	ds_read_b64_tr_b16 v[98:99], v176 offset:0x3c00
	s_waitcnt lgkmcnt(0)
	v_mfma_f32_32x32x16_bf16 v[34:49], v[80:83], v[100:103], v[34:49]
	v_mfma_f32_32x32x16_bf16 v[18:33], v[68:71], v[84:87], v[18:33]
	ds_read_b64_tr_b16 v[84:85], v176 offset:0x600
	ds_read_b64_tr_b16 v[86:87], v176 offset:0xe00
	v_mfma_f32_32x32x16_bf16 v[18:33], v[72:75], v[88:91], v[18:33]
	ds_read_b64_tr_b16 v[88:89], v176 offset:0x1600
	ds_read_b64_tr_b16 v[90:91], v176 offset:0x1e00
	v_mfma_f32_32x32x16_bf16 v[18:33], v[76:79], v[92:95], v[18:33]
	ds_read_b64_tr_b16 v[92:93], v176 offset:0x2600
	ds_read_b64_tr_b16 v[94:95], v176 offset:0x2e00
	ds_read_b64_tr_b16 v[100:101], v176 offset:0x3600
	ds_read_b64_tr_b16 v[102:103], v176 offset:0x3e00
	s_waitcnt lgkmcnt(0)
	v_mfma_f32_32x32x16_bf16 v[18:33], v[80:83], v[96:99], v[18:33]
	v_mfma_f32_32x32x16_bf16 v[2:17], v[68:71], v[84:87], v[2:17]
	s_waitcnt vmcnt(0) lgkmcnt(0)
	v_cmp_gt_u32_e32 vcc, 32, v175
	s_barrier
; DEVI bf16_t f2bf(float x) { return (bf16_t)(cvtpk(x, 0.f) & 0xffffu); }
; DEVI int crow(int r, int hi) { return (r & 3) + 8 * (r >> 2) + 4 * hi; }
; template <bool FIXED>
; DEVI void attn_task(const bf16_t* __restrict__ Qb, const bf16_t* __restrict__ Kh, const bf16_t* __restrict__ Vh, bf16_t* __restrict__ Ob, char* lds, float shiftC) {
;     ...
;   if (hi == 0) li_l[r32] = l_reg;
;   asm volatile("s_waitcnt lgkmcnt(0)" ::: "memory");
;   char* Oc = (char*)Ob;
; #pragma unroll
;   for (int r = 0; r < 16; ++r) {
;     const int orow = crow(r, hi);
;     const float rl = 1.f / li_l[orow];
;     const unsigned ooff = (unsigned)((wid * 32 + orow) * LDP + r32) * 2u;
; #pragma unroll
;     for (int d0 = 0; d0 < 4; ++d0) *(bf16_t*)(Oc + (ooff + d0 * 64)) = f2bf(o[d0][r] * rl);
;   }
	v_mfma_f32_32x32x16_bf16 v[2:17], v[72:75], v[88:91], v[2:17]
	v_mfma_f32_32x32x16_bf16 v[2:17], v[76:79], v[92:95], v[2:17]
	v_mfma_f32_32x32x16_bf16 v[2:17], v[80:83], v[100:103], v[2:17]
	s_and_saveexec_b64 s[26:27], vcc
	v_add_f32_e32 v66, v66, v67
	v_add_f32_e32 v0, v0, v66
	v_lshl_add_u32 v66, v172, 2, v110
	ds_write_b32 v66, v0 offset:40960
	s_or_b64 exec, exec, s[26:27]
	v_lshl_add_u32 v0, v173, 4, v110
	s_waitcnt lgkmcnt(0)
	v_add_u32_e32 v68, 0xa000, v0
	ds_read2_b32 v[70:71], v68 offset1:1
	ds_read2_b32 v[66:67], v68 offset0:2 offset1:3
	ds_read2_b32 v[72:73], v68 offset0:8 offset1:9
	ds_read2_b32 v[74:75], v68 offset0:10 offset1:11
	s_waitcnt lgkmcnt(0)
	v_div_scale_f32 v0, s[26:27], v70, v70, 1.0
	v_rcp_f32_e32 v69, v0
	v_div_scale_f32 v76, vcc, 1.0, v70, 1.0
	v_fma_f32 v77, -v0, v69, 1.0
	v_fmac_f32_e32 v69, v77, v69
	v_mul_f32_e32 v77, v76, v69
	v_fma_f32 v78, -v0, v77, v76
	v_fmac_f32_e32 v77, v78, v69
	v_fma_f32 v0, -v0, v77, v76
	v_div_fmas_f32 v0, v0, v69, v77
	v_div_fixup_f32 v69, v0, v70, 1.0
	v_lshl_or_b32 v0, v173, 2, v174
	v_mul_lo_u32 v70, v0, s47
	v_or_b32_e32 v70, v70, v172
	v_mul_f32_e32 v18, v18, v69
	v_lshlrev_b32_e32 v70, 1, v70
	v_mul_f32_e32 v34, v34, v69
	v_cvt_pk_bf16_f32 v18, v18, v1
	v_cvt_pk_bf16_f32 v34, v34, v1
	global_store_short v70, v18, s[42:43] offset:128
	v_div_scale_f32 v18, s[26:27], v71, v71, 1.0
	global_store_short v70, v34, s[42:43] offset:64
	v_rcp_f32_e32 v34, v18
	v_mul_f32_e32 v2, v2, v69
	v_cvt_pk_bf16_f32 v2, v2, v1
	v_mul_f32_e32 v50, v50, v69
	global_store_short v70, v2, s[42:43] offset:192
	v_fma_f32 v2, -v18, v34, 1.0
	v_cvt_pk_bf16_f32 v50, v50, v1
	v_fmac_f32_e32 v34, v2, v34
	v_div_scale_f32 v2, vcc, 1.0, v71, 1.0
	global_store_short v70, v50, s[42:43]
	v_mul_f32_e32 v50, v2, v34
	v_fma_f32 v69, -v18, v50, v2
	v_fmac_f32_e32 v50, v69, v34
	v_fma_f32 v2, -v18, v50, v2
	v_div_fmas_f32 v2, v2, v34, v50
	v_or_b32_e32 v18, 1, v0
	v_div_fixup_f32 v2, v2, v71, 1.0
	v_mul_lo_u32 v18, v18, s47
	v_or_b32_e32 v18, v18, v172
	v_mul_f32_e32 v34, v51, v2
	v_lshlrev_b32_e32 v18, 1, v18
	v_cvt_pk_bf16_f32 v34, v34, v1
	v_mul_f32_e32 v19, v19, v2
	global_store_short v18, v34, s[42:43]
	v_mul_f32_e32 v34, v35, v2
	v_cvt_pk_bf16_f32 v19, v19, v1
	v_cvt_pk_bf16_f32 v34, v34, v1
	global_store_short v18, v19, s[42:43] offset:128
	v_div_scale_f32 v19, s[26:27], v66, v66, 1.0
	global_store_short v18, v34, s[42:43] offset:64
	v_rcp_f32_e32 v34, v19
	v_mul_f32_e32 v2, v3, v2
	v_cvt_pk_bf16_f32 v2, v2, v1
	global_store_short v18, v2, s[42:43] offset:192
	v_fma_f32 v2, -v19, v34, 1.0
	v_fmac_f32_e32 v34, v2, v34
	v_div_scale_f32 v2, vcc, 1.0, v66, 1.0
	v_mul_f32_e32 v3, v2, v34
	v_fma_f32 v18, -v19, v3, v2
	v_fmac_f32_e32 v3, v18, v34
	v_fma_f32 v2, -v19, v3, v2
	v_div_fmas_f32 v2, v2, v34, v3
	v_or_b32_e32 v3, 2, v0
	v_div_fixup_f32 v2, v2, v66, 1.0
	v_mul_lo_u32 v3, v3, s47
	v_or_b32_e32 v3, v3, v172
	v_mul_f32_e32 v18, v52, v2
	v_lshlrev_b32_e32 v3, 1, v3
	v_cvt_pk_bf16_f32 v18, v18, v1
	global_store_short v3, v18, s[42:43]
	v_mul_f32_e32 v18, v36, v2
	v_cvt_pk_bf16_f32 v18, v18, v1
	global_store_short v3, v18, s[42:43] offset:64
	v_mul_f32_e32 v18, v20, v2
	v_cvt_pk_bf16_f32 v18, v18, v1
	global_store_short v3, v18, s[42:43] offset:128
	v_div_scale_f32 v18, s[26:27], v67, v67, 1.0
	v_rcp_f32_e32 v19, v18
	v_mul_f32_e32 v2, v4, v2
	v_cvt_pk_bf16_f32 v2, v2, v1
	global_store_short v3, v2, s[42:43] offset:192
	v_fma_f32 v2, -v18, v19, 1.0
	v_fmac_f32_e32 v19, v2, v19
	v_div_scale_f32 v2, vcc, 1.0, v67, 1.0
	v_mul_f32_e32 v3, v2, v19
	v_fma_f32 v4, -v18, v3, v2
	v_fmac_f32_e32 v3, v4, v19
	v_fma_f32 v2, -v18, v3, v2
	v_div_fmas_f32 v2, v2, v19, v3
	v_or_b32_e32 v3, 3, v0
	v_div_fixup_f32 v2, v2, v67, 1.0
	v_mul_lo_u32 v3, v3, s47
	v_or_b32_e32 v3, v3, v172
	v_mul_f32_e32 v4, v53, v2
	v_lshlrev_b32_e32 v3, 1, v3
	v_cvt_pk_bf16_f32 v4, v4, v1
	global_store_short v3, v4, s[42:43]
	v_mul_f32_e32 v4, v37, v2
	v_cvt_pk_bf16_f32 v4, v4, v1
	global_store_short v3, v4, s[42:43] offset:64
	v_mul_f32_e32 v4, v21, v2
	v_cvt_pk_bf16_f32 v4, v4, v1
	v_add_u32_e32 v18, 0x80, v3
	global_store_short v18, v4, s[42:43]
	v_div_scale_f32 v4, s[26:27], v72, v72, 1.0
	v_mul_f32_e32 v2, v5, v2
	v_rcp_f32_e32 v5, v4
	v_cvt_pk_bf16_f32 v2, v2, v1
	v_add_u32_e32 v3, 0xc0, v3
	global_store_short v3, v2, s[42:43]
	v_fma_f32 v2, -v4, v5, 1.0
	v_fmac_f32_e32 v5, v2, v5
	v_div_scale_f32 v2, vcc, 1.0, v72, 1.0
	v_mul_f32_e32 v3, v2, v5
	v_fma_f32 v18, -v4, v3, v2
	v_fmac_f32_e32 v3, v18, v5
	v_fma_f32 v2, -v4, v3, v2
	v_div_fmas_f32 v2, v2, v5, v3
	v_or_b32_e32 v3, 8, v0
	v_div_fixup_f32 v2, v2, v72, 1.0
	v_mul_lo_u32 v3, v3, s47
	v_or_b32_e32 v3, v3, v172
	v_mul_f32_e32 v4, v54, v2
	v_lshlrev_b32_e32 v3, 1, v3
	v_cvt_pk_bf16_f32 v4, v4, v1
	global_store_short v3, v4, s[42:43]
	v_mul_f32_e32 v4, v38, v2
	v_cvt_pk_bf16_f32 v4, v4, v1
	global_store_short v3, v4, s[42:43] offset:64
	v_mul_f32_e32 v4, v22, v2
	v_cvt_pk_bf16_f32 v4, v4, v1
	global_store_short v3, v4, s[42:43] offset:128
	v_div_scale_f32 v4, s[26:27], v73, v73, 1.0
	v_rcp_f32_e32 v5, v4
	v_mul_f32_e32 v2, v6, v2
	v_cvt_pk_bf16_f32 v2, v2, v1
	global_store_short v3, v2, s[42:43] offset:192
	v_fma_f32 v2, -v4, v5, 1.0
	v_fmac_f32_e32 v5, v2, v5
	v_div_scale_f32 v2, vcc, 1.0, v73, 1.0
	v_mul_f32_e32 v3, v2, v5
	v_fma_f32 v6, -v4, v3, v2
	v_fmac_f32_e32 v3, v6, v5
	v_fma_f32 v2, -v4, v3, v2
	v_div_fmas_f32 v2, v2, v5, v3
	v_or_b32_e32 v3, 9, v0
	v_div_fixup_f32 v2, v2, v73, 1.0
	v_mul_lo_u32 v3, v3, s47
	v_or_b32_e32 v3, v3, v172
	v_mul_f32_e32 v4, v55, v2
	v_lshlrev_b32_e32 v3, 1, v3
	v_cvt_pk_bf16_f32 v4, v4, v1
	global_store_short v3, v4, s[42:43]
	v_mul_f32_e32 v4, v39, v2
; DEVI bf16_t f2bf(float x) { return (bf16_t)(cvtpk(x, 0.f) & 0xffffu); }
; DEVI int crow(int r, int hi) { return (r & 3) + 8 * (r >> 2) + 4 * hi; }
; template <bool FIXED>
; DEVI void attn_task(const bf16_t* __restrict__ Qb, const bf16_t* __restrict__ Kh, const bf16_t* __restrict__ Vh, bf16_t* __restrict__ Ob, char* lds, float shiftC) {
;     ...
;   for (int r = 0; r < 16; ++r) {
;     const int orow = crow(r, hi);
;     const float rl = 1.f / li_l[orow];
;     const unsigned ooff = (unsigned)((wid * 32 + orow) * LDP + r32) * 2u;
; #pragma unroll
;     for (int d0 = 0; d0 < 4; ++d0) *(bf16_t*)(Oc + (ooff + d0 * 64)) = f2bf(o[d0][r] * rl);
;   }
	v_cvt_pk_bf16_f32 v4, v4, v1
	global_store_short v3, v4, s[42:43] offset:64
	v_mul_f32_e32 v4, v23, v2
	v_cvt_pk_bf16_f32 v4, v4, v1
	global_store_short v3, v4, s[42:43] offset:128
	v_div_scale_f32 v4, s[26:27], v74, v74, 1.0
	v_rcp_f32_e32 v5, v4
	v_mul_f32_e32 v2, v7, v2
	v_cvt_pk_bf16_f32 v2, v2, v1
	global_store_short v3, v2, s[42:43] offset:192
	v_fma_f32 v2, -v4, v5, 1.0
	v_fmac_f32_e32 v5, v2, v5
	v_div_scale_f32 v2, vcc, 1.0, v74, 1.0
	v_mul_f32_e32 v3, v2, v5
	v_fma_f32 v6, -v4, v3, v2
	v_fmac_f32_e32 v3, v6, v5
	v_fma_f32 v2, -v4, v3, v2
	v_div_fmas_f32 v2, v2, v5, v3
	v_or_b32_e32 v3, 10, v0
	v_div_fixup_f32 v2, v2, v74, 1.0
	v_mul_lo_u32 v3, v3, s47
	v_or_b32_e32 v3, v3, v172
	v_mul_f32_e32 v4, v56, v2
	v_lshlrev_b32_e32 v3, 1, v3
	v_cvt_pk_bf16_f32 v4, v4, v1
	global_store_short v3, v4, s[42:43]
	v_mul_f32_e32 v4, v40, v2
	v_cvt_pk_bf16_f32 v4, v4, v1
	global_store_short v3, v4, s[42:43] offset:64
	v_mul_f32_e32 v4, v24, v2
	v_cvt_pk_bf16_f32 v4, v4, v1
	global_store_short v3, v4, s[42:43] offset:128
	v_div_scale_f32 v4, s[26:27], v75, v75, 1.0
	v_rcp_f32_e32 v5, v4
	v_mul_f32_e32 v2, v8, v2
	v_cvt_pk_bf16_f32 v2, v2, v1
	global_store_short v3, v2, s[42:43] offset:192
	v_fma_f32 v2, -v4, v5, 1.0
	v_fmac_f32_e32 v5, v2, v5
	v_div_scale_f32 v2, vcc, 1.0, v75, 1.0
	v_mul_f32_e32 v3, v2, v5
	v_fma_f32 v6, -v4, v3, v2
	v_fmac_f32_e32 v3, v6, v5
	v_fma_f32 v2, -v4, v3, v2
	v_div_fmas_f32 v2, v2, v5, v3
	v_or_b32_e32 v3, 11, v0
	v_mul_lo_u32 v3, v3, s47
	v_div_fixup_f32 v2, v2, v75, 1.0
	v_or_b32_e32 v3, v3, v172
	v_lshlrev_b32_e32 v18, 1, v3
	v_mul_f32_e32 v3, v57, v2
	v_cvt_pk_bf16_f32 v3, v3, v1
	global_store_short v18, v3, s[42:43]
	v_mul_f32_e32 v3, v41, v2
	v_cvt_pk_bf16_f32 v3, v3, v1
	global_store_short v18, v3, s[42:43] offset:64
	v_mul_f32_e32 v3, v25, v2
	v_add_u32_e32 v4, 0x80, v18
	v_cvt_pk_bf16_f32 v3, v3, v1
	global_store_short v4, v3, s[42:43]
	v_mul_f32_e32 v19, v9, v2
	ds_read2_b32 v[2:3], v68 offset0:16 offset1:17
	ds_read2_b32 v[4:5], v68 offset0:18 offset1:19
	ds_read2_b32 v[6:7], v68 offset0:24 offset1:25
	ds_read2_b32 v[8:9], v68 offset0:26 offset1:27
	v_add_u32_e32 v18, 0xc0, v18
	s_waitcnt lgkmcnt(0)
	v_div_scale_f32 v20, s[26:27], v2, v2, 1.0
	v_rcp_f32_e32 v21, v20
	v_cvt_pk_bf16_f32 v19, v19, v1
	global_store_short v18, v19, s[42:43]
	v_fma_f32 v18, -v20, v21, 1.0
	v_fmac_f32_e32 v21, v18, v21
	v_div_scale_f32 v18, vcc, 1.0, v2, 1.0
	v_mul_f32_e32 v19, v18, v21
	v_fma_f32 v22, -v20, v19, v18
	v_fmac_f32_e32 v19, v22, v21
	v_fma_f32 v18, -v20, v19, v18
	v_div_fmas_f32 v18, v18, v21, v19
	v_div_fixup_f32 v2, v18, v2, 1.0
	v_or_b32_e32 v18, 16, v0
	v_mul_lo_u32 v18, v18, s47
	v_or_b32_e32 v18, v18, v172
	v_mul_f32_e32 v19, v58, v2
	v_lshlrev_b32_e32 v18, 1, v18
	v_cvt_pk_bf16_f32 v19, v19, v1
	global_store_short v18, v19, s[42:43]
	v_mul_f32_e32 v19, v42, v2
	v_cvt_pk_bf16_f32 v19, v19, v1
	global_store_short v18, v19, s[42:43] offset:64
	v_mul_f32_e32 v19, v26, v2
	v_cvt_pk_bf16_f32 v19, v19, v1
	global_store_short v18, v19, s[42:43] offset:128
	v_div_scale_f32 v19, s[26:27], v3, v3, 1.0
	v_rcp_f32_e32 v20, v19
	v_mul_f32_e32 v2, v10, v2
	v_cvt_pk_bf16_f32 v2, v2, v1
	global_store_short v18, v2, s[42:43] offset:192
	v_fma_f32 v2, -v19, v20, 1.0
	v_fmac_f32_e32 v20, v2, v20
	v_div_scale_f32 v2, vcc, 1.0, v3, 1.0
	v_mul_f32_e32 v10, v2, v20
	v_fma_f32 v18, -v19, v10, v2
	v_fmac_f32_e32 v10, v18, v20
	v_fma_f32 v2, -v19, v10, v2
	v_div_fmas_f32 v2, v2, v20, v10
	v_div_fixup_f32 v2, v2, v3, 1.0
	v_or_b32_e32 v3, 17, v0
	v_mul_lo_u32 v3, v3, s47
	v_or_b32_e32 v3, v3, v172
	v_mul_f32_e32 v10, v59, v2
	v_lshlrev_b32_e32 v3, 1, v3
	v_cvt_pk_bf16_f32 v10, v10, v1
	global_store_short v3, v10, s[42:43]
	v_mul_f32_e32 v10, v43, v2
	v_cvt_pk_bf16_f32 v10, v10, v1
	global_store_short v3, v10, s[42:43] offset:64
	v_mul_f32_e32 v10, v27, v2
	v_cvt_pk_bf16_f32 v10, v10, v1
	global_store_short v3, v10, s[42:43] offset:128
	v_div_scale_f32 v10, s[26:27], v4, v4, 1.0
	v_rcp_f32_e32 v18, v10
	v_mul_f32_e32 v2, v11, v2
	v_cvt_pk_bf16_f32 v2, v2, v1
	global_store_short v3, v2, s[42:43] offset:192
	v_fma_f32 v2, -v10, v18, 1.0
	v_fmac_f32_e32 v18, v2, v18
	v_div_scale_f32 v2, vcc, 1.0, v4, 1.0
	v_mul_f32_e32 v3, v2, v18
	v_fma_f32 v11, -v10, v3, v2
	v_fmac_f32_e32 v3, v11, v18
	v_fma_f32 v2, -v10, v3, v2
	v_div_fmas_f32 v2, v2, v18, v3
	v_or_b32_e32 v3, 18, v0
	v_div_fixup_f32 v2, v2, v4, 1.0
	v_mul_lo_u32 v3, v3, s47
	v_or_b32_e32 v3, v3, v172
	v_mul_f32_e32 v4, v60, v2
	v_lshlrev_b32_e32 v3, 1, v3
	v_cvt_pk_bf16_f32 v4, v4, v1
	global_store_short v3, v4, s[42:43]
	v_mul_f32_e32 v4, v44, v2
	v_cvt_pk_bf16_f32 v4, v4, v1
; DEVI bf16_t f2bf(float x) { return (bf16_t)(cvtpk(x, 0.f) & 0xffffu); }
; DEVI int crow(int r, int hi) { return (r & 3) + 8 * (r >> 2) + 4 * hi; }
; template <bool FIXED>
; DEVI void attn_task(const bf16_t* __restrict__ Qb, const bf16_t* __restrict__ Kh, const bf16_t* __restrict__ Vh, bf16_t* __restrict__ Ob, char* lds, float shiftC) {
;     ...
;   for (int r = 0; r < 16; ++r) {
;     const int orow = crow(r, hi);
;     const float rl = 1.f / li_l[orow];
;     const unsigned ooff = (unsigned)((wid * 32 + orow) * LDP + r32) * 2u;
; #pragma unroll
;     for (int d0 = 0; d0 < 4; ++d0) *(bf16_t*)(Oc + (ooff + d0 * 64)) = f2bf(o[d0][r] * rl);
;   }
;   __syncthreads();
	global_store_short v3, v4, s[42:43] offset:64
	v_mul_f32_e32 v4, v28, v2
	v_cvt_pk_bf16_f32 v4, v4, v1
	global_store_short v3, v4, s[42:43] offset:128
	v_div_scale_f32 v4, s[26:27], v5, v5, 1.0
	v_rcp_f32_e32 v10, v4
	v_mul_f32_e32 v2, v12, v2
	v_cvt_pk_bf16_f32 v2, v2, v1
	global_store_short v3, v2, s[42:43] offset:192
	v_fma_f32 v2, -v4, v10, 1.0
	v_fmac_f32_e32 v10, v2, v10
	v_div_scale_f32 v2, vcc, 1.0, v5, 1.0
	v_mul_f32_e32 v3, v2, v10
	v_fma_f32 v11, -v4, v3, v2
	v_fmac_f32_e32 v3, v11, v10
	v_fma_f32 v2, -v4, v3, v2
	v_div_fmas_f32 v2, v2, v10, v3
	v_or_b32_e32 v3, 19, v0
	v_div_fixup_f32 v2, v2, v5, 1.0
	v_mul_lo_u32 v3, v3, s47
	v_or_b32_e32 v3, v3, v172
	v_mul_f32_e32 v4, v61, v2
	v_lshlrev_b32_e32 v3, 1, v3
	v_cvt_pk_bf16_f32 v4, v4, v1
	global_store_short v3, v4, s[42:43]
	v_mul_f32_e32 v4, v45, v2
	v_cvt_pk_bf16_f32 v4, v4, v1
	global_store_short v3, v4, s[42:43] offset:64
	v_mul_f32_e32 v4, v29, v2
	v_cvt_pk_bf16_f32 v4, v4, v1
	v_add_u32_e32 v5, 0x80, v3
	global_store_short v5, v4, s[42:43]
	v_div_scale_f32 v4, s[26:27], v6, v6, 1.0
	v_rcp_f32_e32 v5, v4
	v_mul_f32_e32 v2, v13, v2
	v_cvt_pk_bf16_f32 v2, v2, v1
	v_add_u32_e32 v3, 0xc0, v3
	global_store_short v3, v2, s[42:43]
	v_fma_f32 v2, -v4, v5, 1.0
	v_fmac_f32_e32 v5, v2, v5
	v_div_scale_f32 v2, vcc, 1.0, v6, 1.0
	v_mul_f32_e32 v3, v2, v5
	v_fma_f32 v10, -v4, v3, v2
	v_fmac_f32_e32 v3, v10, v5
	v_fma_f32 v2, -v4, v3, v2
	v_div_fmas_f32 v2, v2, v5, v3
	v_or_b32_e32 v3, 24, v0
	v_div_fixup_f32 v2, v2, v6, 1.0
	v_mul_lo_u32 v3, v3, s47
	v_or_b32_e32 v3, v3, v172
	v_mul_f32_e32 v4, v62, v2
	v_lshlrev_b32_e32 v3, 1, v3
	v_cvt_pk_bf16_f32 v4, v4, v1
	global_store_short v3, v4, s[42:43]
	v_mul_f32_e32 v4, v46, v2
	v_cvt_pk_bf16_f32 v4, v4, v1
	global_store_short v3, v4, s[42:43] offset:64
	v_mul_f32_e32 v4, v30, v2
	v_cvt_pk_bf16_f32 v4, v4, v1
	global_store_short v3, v4, s[42:43] offset:128
	v_div_scale_f32 v4, s[26:27], v7, v7, 1.0
	v_rcp_f32_e32 v5, v4
	v_mul_f32_e32 v2, v14, v2
	v_cvt_pk_bf16_f32 v2, v2, v1
	global_store_short v3, v2, s[42:43] offset:192
	v_fma_f32 v2, -v4, v5, 1.0
	v_fmac_f32_e32 v5, v2, v5
	v_div_scale_f32 v2, vcc, 1.0, v7, 1.0
	v_mul_f32_e32 v3, v2, v5
	v_fma_f32 v6, -v4, v3, v2
	v_fmac_f32_e32 v3, v6, v5
	v_fma_f32 v2, -v4, v3, v2
	v_div_fmas_f32 v2, v2, v5, v3
	v_or_b32_e32 v3, 25, v0
	v_div_fixup_f32 v2, v2, v7, 1.0
	v_mul_lo_u32 v3, v3, s47
	v_or_b32_e32 v3, v3, v172
	v_mul_f32_e32 v4, v63, v2
	v_lshlrev_b32_e32 v3, 1, v3
	v_cvt_pk_bf16_f32 v4, v4, v1
	global_store_short v3, v4, s[42:43]
	v_mul_f32_e32 v4, v47, v2
	v_cvt_pk_bf16_f32 v4, v4, v1
	global_store_short v3, v4, s[42:43] offset:64
	v_mul_f32_e32 v4, v31, v2
	v_cvt_pk_bf16_f32 v4, v4, v1
	global_store_short v3, v4, s[42:43] offset:128
	v_div_scale_f32 v4, s[26:27], v8, v8, 1.0
	v_rcp_f32_e32 v5, v4
	v_mul_f32_e32 v2, v15, v2
	v_cvt_pk_bf16_f32 v2, v2, v1
	global_store_short v3, v2, s[42:43] offset:192
	v_fma_f32 v2, -v4, v5, 1.0
	v_fmac_f32_e32 v5, v2, v5
	v_div_scale_f32 v2, vcc, 1.0, v8, 1.0
	v_mul_f32_e32 v3, v2, v5
	v_fma_f32 v6, -v4, v3, v2
	v_fmac_f32_e32 v3, v6, v5
	v_fma_f32 v2, -v4, v3, v2
	v_div_fmas_f32 v2, v2, v5, v3
	v_or_b32_e32 v3, 26, v0
	v_div_fixup_f32 v2, v2, v8, 1.0
	v_mul_lo_u32 v3, v3, s47
	v_or_b32_e32 v3, v3, v172
	v_mul_f32_e32 v4, v64, v2
	v_lshlrev_b32_e32 v3, 1, v3
	v_cvt_pk_bf16_f32 v4, v4, v1
	global_store_short v3, v4, s[42:43]
	v_mul_f32_e32 v4, v48, v2
	v_cvt_pk_bf16_f32 v4, v4, v1
	global_store_short v3, v4, s[42:43] offset:64
	v_mul_f32_e32 v4, v32, v2
	v_cvt_pk_bf16_f32 v4, v4, v1
	global_store_short v3, v4, s[42:43] offset:128
	v_div_scale_f32 v4, s[26:27], v9, v9, 1.0
	v_rcp_f32_e32 v5, v4
	v_mul_f32_e32 v2, v16, v2
	v_cvt_pk_bf16_f32 v2, v2, v1
	global_store_short v3, v2, s[42:43] offset:192
	v_fma_f32 v2, -v4, v5, 1.0
	v_fmac_f32_e32 v5, v2, v5
	v_div_scale_f32 v2, vcc, 1.0, v9, 1.0
	v_mul_f32_e32 v3, v2, v5
	v_fma_f32 v6, -v4, v3, v2
	v_fmac_f32_e32 v3, v6, v5
	v_fma_f32 v2, -v4, v3, v2
	v_div_fmas_f32 v2, v2, v5, v3
	v_or_b32_e32 v0, 27, v0
	v_div_fixup_f32 v2, v2, v9, 1.0
	v_mul_lo_u32 v0, v0, s47
	v_or_b32_e32 v0, v0, v172
	v_mul_f32_e32 v3, v65, v2
	v_lshlrev_b32_e32 v0, 1, v0
	v_cvt_pk_bf16_f32 v3, v3, v1
	global_store_short v0, v3, s[42:43]
	v_mul_f32_e32 v3, v49, v2
	v_cvt_pk_bf16_f32 v3, v3, v1
	global_store_short v0, v3, s[42:43] offset:64
	v_mul_f32_e32 v3, v33, v2
	v_add_u32_e32 v4, 0x80, v0
	v_mul_f32_e32 v2, v17, v2
	v_add_u32_e32 v0, 0xc0, v0
	s_mov_b64 s[26:27], 0
	v_cvt_pk_bf16_f32 v3, v3, v1
	global_store_short v4, v3, s[42:43]
	v_cvt_pk_bf16_f32 v2, v2, v1
	global_store_short v0, v2, s[42:43]
	s_waitcnt vmcnt(0)
	s_barrier

; #define GBAR() do { asm volatile("s_waitcnt vmcnt(0) lgkmcnt(0)" ::: "memory"); __builtin_amdgcn_s_barrier(); } while (0)
; template <int EPI, bool GUARD>
; DEVI void gemm_tile(const Params& p, const bf16_t* __restrict__ A, int lda, const bf16_t* __restrict__ Bt, int ldb, int K,
;                           int row_base, int row_lo, int row_hi, int tile_n, int layer, int which, char* lds) {
;     ...
;   const int swz = c16 >> 1;
;   int koff[2];
; #pragma unroll
;   for (int ks = 0; ks < 2; ++ks) koff[ks] = ((ks * 4 + q4) ^ swz) << 4;
;   const int arow = (wr * 64 + c16) * 128, brow = 16384 + (wc * 64 + c16) * 128;
;     ...
;   GISSUE(0, 0); GBAR();
;   for (int k0 = 0; k0 < K; k0 += 128) {
;     GISSUE(k0 + 64, 1);
;     KSTEPS(0);
;     GBAR();
;     if (k0 + 128 < K) GISSUE(k0 + 128, 0);
;     KSTEPS(1);
;     GBAR();
;   }
.LBB0_1258:
	ds_read_b128 v[82:85], v64 offset:32768
	ds_read_b128 v[86:89], v112 offset:49152
	ds_read_b128 v[90:93], v64 offset:34816
	ds_read_b128 v[94:97], v112 offset:51200
	ds_read_b128 v[116:119], v112 offset:53248
	ds_read_b128 v[120:123], v112 offset:55296
	s_addk_i32 s51, 0x80
	s_waitcnt lgkmcnt(0)
	v_mfma_f32_16x16x32_bf16 v[0:3], v[82:85], v[86:89], v[0:3]
	s_add_u32 s2, s2, 0x100
	s_addc_u32 s3, s3, 0
	s_and_b64 vcc, exec, s[4:5]
	v_mfma_f32_16x16x32_bf16 v[4:7], v[82:85], v[94:97], v[4:7]
	v_mfma_f32_16x16x32_bf16 v[8:11], v[82:85], v[116:119], v[8:11]
	v_mfma_f32_16x16x32_bf16 v[12:15], v[82:85], v[120:123], v[12:15]
	v_mfma_f32_16x16x32_bf16 v[82:85], v[90:93], v[86:89], v[16:19]
	v_mfma_f32_16x16x32_bf16 v[20:23], v[90:93], v[94:97], v[20:23]
	v_mfma_f32_16x16x32_bf16 v[24:27], v[90:93], v[116:119], v[24:27]
	v_mfma_f32_16x16x32_bf16 v[28:31], v[90:93], v[120:123], v[28:31]
	ds_read_b128 v[16:19], v64 offset:36864
	ds_read_b128 v[90:93], v64 offset:38912
	s_waitcnt lgkmcnt(0)
	v_mfma_f32_16x16x32_bf16 v[124:127], v[16:19], v[86:89], v[32:35]
	v_mfma_f32_16x16x32_bf16 v[36:39], v[16:19], v[94:97], v[36:39]
	v_mfma_f32_16x16x32_bf16 v[40:43], v[16:19], v[116:119], v[40:43]
	v_mfma_f32_16x16x32_bf16 v[44:47], v[16:19], v[120:123], v[44:47]
	ds_read_b128 v[16:19], v113 offset:32768
	v_mfma_f32_16x16x32_bf16 v[86:89], v[90:93], v[86:89], v[48:51]
	v_mfma_f32_16x16x32_bf16 v[52:55], v[90:93], v[94:97], v[52:55]
	v_mfma_f32_16x16x32_bf16 v[56:59], v[90:93], v[116:119], v[56:59]
	v_mfma_f32_16x16x32_bf16 v[60:63], v[90:93], v[120:123], v[60:63]
	ds_read_b128 v[90:93], v114 offset:49152
	ds_read_b128 v[32:35], v113 offset:34816
	ds_read_b128 v[94:97], v114 offset:51200
	ds_read_b128 v[116:119], v114 offset:53248
	ds_read_b128 v[120:123], v114 offset:55296
	s_waitcnt lgkmcnt(0)
	v_mfma_f32_16x16x32_bf16 v[0:3], v[16:19], v[90:93], v[0:3]
	v_mfma_f32_16x16x32_bf16 v[4:7], v[16:19], v[94:97], v[4:7]
	v_mfma_f32_16x16x32_bf16 v[8:11], v[16:19], v[116:119], v[8:11]
	v_mfma_f32_16x16x32_bf16 v[16:19], v[16:19], v[120:123], v[12:15]
	v_mfma_f32_16x16x32_bf16 v[12:15], v[32:35], v[90:93], v[82:85]
	ds_read_b128 v[48:51], v113 offset:36864
	s_nop 1
	ds_read_b128 v[82:85], v113 offset:38912
	s_waitcnt vmcnt(0) lgkmcnt(0)
	s_barrier
	s_cbranch_vccnz .Lge6_exit1
	v_mfma_f32_16x16x32_bf16 v[20:23], v[32:35], v[94:97], v[20:23]
	s_add_i32 m0, s52, 0x8000
	v_lshl_add_u64 v[246:247], s[2:3], 0, v[66:67]
	v_lshl_add_u64 v[246:247], v[246:247], 0, s[18:19]
	global_load_lds_dwordx4 v[246:247], off
	v_mfma_f32_16x16x32_bf16 v[24:27], v[32:35], v[116:119], v[24:27]
	s_add_i32 m0, s52, 0xc000
	v_lshl_add_u64 v[246:247], s[2:3], 0, v[74:75]
	v_lshl_add_u64 v[246:247], v[246:247], 0, s[26:27]
	global_load_lds_dwordx4 v[246:247], off
	v_mfma_f32_16x16x32_bf16 v[32:35], v[32:35], v[120:123], v[28:31]
	s_add_i32 m0, s52, 0x8400
	v_lshl_add_u64 v[246:247], s[2:3], 0, v[68:69]
	v_lshl_add_u64 v[246:247], v[246:247], 0, s[18:19]
	global_load_lds_dwordx4 v[246:247], off
	s_waitcnt lgkmcnt(0)
	v_mfma_f32_16x16x32_bf16 v[28:31], v[48:51], v[90:93], v[124:127]
	s_add_i32 m0, s52, 0xc400
	v_lshl_add_u64 v[246:247], s[2:3], 0, v[76:77]
	v_lshl_add_u64 v[246:247], v[246:247], 0, s[26:27]
	global_load_lds_dwordx4 v[246:247], off
	v_mfma_f32_16x16x32_bf16 v[36:39], v[48:51], v[94:97], v[36:39]
	s_add_i32 m0, s52, 0x8800
	v_lshl_add_u64 v[246:247], s[2:3], 0, v[70:71]
	v_lshl_add_u64 v[246:247], v[246:247], 0, s[18:19]
	global_load_lds_dwordx4 v[246:247], off
	v_mfma_f32_16x16x32_bf16 v[40:43], v[48:51], v[116:119], v[40:43]
	s_add_i32 m0, s52, 0xc800
	v_lshl_add_u64 v[246:247], s[2:3], 0, v[78:79]
	v_lshl_add_u64 v[246:247], v[246:247], 0, s[26:27]
	global_load_lds_dwordx4 v[246:247], off
	v_mfma_f32_16x16x32_bf16 v[48:51], v[48:51], v[120:123], v[44:47]
	s_add_i32 m0, s58, 0x8000
	v_lshl_add_u64 v[246:247], s[2:3], 0, v[72:73]
	v_lshl_add_u64 v[246:247], v[246:247], 0, s[18:19]
	global_load_lds_dwordx4 v[246:247], off
	v_mfma_f32_16x16x32_bf16 v[44:47], v[82:85], v[90:93], v[86:89]
	s_add_i32 m0, s58, 0xc000
	v_lshl_add_u64 v[246:247], s[2:3], 0, v[80:81]
	v_lshl_add_u64 v[246:247], v[246:247], 0, s[26:27]
	global_load_lds_dwordx4 v[246:247], off
	v_mfma_f32_16x16x32_bf16 v[52:55], v[82:85], v[94:97], v[52:55]
	v_mfma_f32_16x16x32_bf16 v[56:59], v[82:85], v[116:119], v[56:59]
	v_mfma_f32_16x16x32_bf16 v[60:63], v[82:85], v[120:123], v[60:63]
	s_cmpk_gt_u32 s51, 0x37f
	s_branch .Lge6_k0
.Lge6_exit1:
	v_mfma_f32_16x16x32_bf16 v[20:23], v[32:35], v[94:97], v[20:23]
	v_mfma_f32_16x16x32_bf16 v[24:27], v[32:35], v[116:119], v[24:27]
	v_mfma_f32_16x16x32_bf16 v[32:35], v[32:35], v[120:123], v[28:31]
	s_waitcnt lgkmcnt(0)
	v_mfma_f32_16x16x32_bf16 v[28:31], v[48:51], v[90:93], v[124:127]
	v_mfma_f32_16x16x32_bf16 v[36:39], v[48:51], v[94:97], v[36:39]
	v_mfma_f32_16x16x32_bf16 v[40:43], v[48:51], v[116:119], v[40:43]
	v_mfma_f32_16x16x32_bf16 v[48:51], v[48:51], v[120:123], v[44:47]
	v_mfma_f32_16x16x32_bf16 v[44:47], v[82:85], v[90:93], v[86:89]
	v_mfma_f32_16x16x32_bf16 v[52:55], v[82:85], v[94:97], v[52:55]
	v_mfma_f32_16x16x32_bf16 v[56:59], v[82:85], v[116:119], v[56:59]
	v_mfma_f32_16x16x32_bf16 v[60:63], v[82:85], v[120:123], v[60:63]
	s_branch .LBB0_1261

; #define GBAR() do { asm volatile("s_waitcnt vmcnt(0) lgkmcnt(0)" ::: "memory"); __builtin_amdgcn_s_barrier(); } while (0)
; template <int EPI, bool GUARD>
; DEVI void gemm_tile(const Params& p, const bf16_t* __restrict__ A, int lda, const bf16_t* __restrict__ Bt, int ldb, int K,
;                           int row_base, int row_lo, int row_hi, int tile_n, int layer, int which, char* lds) {
;     ...
;   const int swz = c16 >> 1;
;   int koff[2];
; #pragma unroll
;   for (int ks = 0; ks < 2; ++ks) koff[ks] = ((ks * 4 + q4) ^ swz) << 4;
;   const int arow = (wr * 64 + c16) * 128, brow = 16384 + (wc * 64 + c16) * 128;
;     ...
;   GISSUE(0, 0); GBAR();
;   for (int k0 = 0; k0 < K; k0 += 128) {
;     GISSUE(k0 + 64, 1);
;     KSTEPS(0);
;     GBAR();
;     if (k0 + 128 < K) GISSUE(k0 + 128, 0);
;     KSTEPS(1);
;     GBAR();
;   }
.Lge6_k0:
	ds_read_b128 v[116:119], v64
	ds_read_b128 v[120:123], v112 offset:16384
	ds_read_b128 v[124:127], v64 offset:2048
	ds_read_b128 v[128:131], v112 offset:18432
	ds_read_b128 v[132:135], v112 offset:20480
	ds_read_b128 v[136:139], v112 offset:22528
	s_waitcnt lgkmcnt(0)
	v_mfma_f32_16x16x32_bf16 v[0:3], v[116:119], v[120:123], v[0:3]
	s_cselect_b64 s[4:5], -1, 0
	s_and_b64 vcc, exec, s[4:5]
	v_mfma_f32_16x16x32_bf16 v[4:7], v[116:119], v[128:131], v[4:7]
	v_mfma_f32_16x16x32_bf16 v[8:11], v[116:119], v[132:135], v[8:11]
	v_mfma_f32_16x16x32_bf16 v[16:19], v[116:119], v[136:139], v[16:19]
	v_mfma_f32_16x16x32_bf16 v[116:119], v[124:127], v[120:123], v[12:15]
	v_mfma_f32_16x16x32_bf16 v[20:23], v[124:127], v[128:131], v[20:23]
	v_mfma_f32_16x16x32_bf16 v[24:27], v[124:127], v[132:135], v[24:27]
	v_mfma_f32_16x16x32_bf16 v[32:35], v[124:127], v[136:139], v[32:35]
	ds_read_b128 v[12:15], v64 offset:4096
	ds_read_b128 v[124:127], v64 offset:6144
	s_waitcnt lgkmcnt(0)
	v_mfma_f32_16x16x32_bf16 v[140:143], v[12:15], v[120:123], v[28:31]
	v_mfma_f32_16x16x32_bf16 v[36:39], v[12:15], v[128:131], v[36:39]
	v_mfma_f32_16x16x32_bf16 v[40:43], v[12:15], v[132:135], v[40:43]
	v_mfma_f32_16x16x32_bf16 v[48:51], v[12:15], v[136:139], v[48:51]
	ds_read_b128 v[12:15], v113
	v_mfma_f32_16x16x32_bf16 v[120:123], v[124:127], v[120:123], v[44:47]
	v_mfma_f32_16x16x32_bf16 v[52:55], v[124:127], v[128:131], v[52:55]
	v_mfma_f32_16x16x32_bf16 v[56:59], v[124:127], v[132:135], v[56:59]
	v_mfma_f32_16x16x32_bf16 v[60:63], v[124:127], v[136:139], v[60:63]
	ds_read_b128 v[124:127], v114 offset:16384
	ds_read_b128 v[28:31], v113 offset:2048
	ds_read_b128 v[128:131], v114 offset:18432
	ds_read_b128 v[132:135], v114 offset:20480
	ds_read_b128 v[136:139], v114 offset:22528
	s_waitcnt lgkmcnt(0)
	v_mfma_f32_16x16x32_bf16 v[0:3], v[12:15], v[124:127], v[0:3]
	v_mfma_f32_16x16x32_bf16 v[4:7], v[12:15], v[128:131], v[4:7]
	v_mfma_f32_16x16x32_bf16 v[8:11], v[12:15], v[132:135], v[8:11]
	v_mfma_f32_16x16x32_bf16 v[12:15], v[12:15], v[136:139], v[16:19]
	v_mfma_f32_16x16x32_bf16 v[16:19], v[28:31], v[124:127], v[116:119]
	ds_read_b128 v[44:47], v113 offset:4096
	s_nop 1
	ds_read_b128 v[116:119], v113 offset:6144
	s_waitcnt vmcnt(0) lgkmcnt(0)
	s_barrier
	s_cbranch_vccnz .Lge6_last0
	v_mfma_f32_16x16x32_bf16 v[20:23], v[28:31], v[128:131], v[20:23]
	s_mov_b32 m0, s52
	v_lshl_add_u64 v[246:247], s[2:3], 0, v[66:67]
	v_lshl_add_u64 v[246:247], v[246:247], 0, s[28:29]
	global_load_lds_dwordx4 v[246:247], off
	v_mfma_f32_16x16x32_bf16 v[24:27], v[28:31], v[132:135], v[24:27]
	s_mov_b32 m0, s53
	v_lshl_add_u64 v[246:247], s[2:3], 0, v[74:75]
	v_lshl_add_u64 v[246:247], v[246:247], 0, s[30:31]
	global_load_lds_dwordx4 v[246:247], off
	v_mfma_f32_16x16x32_bf16 v[28:31], v[28:31], v[136:139], v[32:35]
	s_mov_b32 m0, s54
	v_lshl_add_u64 v[246:247], s[2:3], 0, v[68:69]
	v_lshl_add_u64 v[246:247], v[246:247], 0, s[28:29]
	global_load_lds_dwordx4 v[246:247], off
	s_waitcnt lgkmcnt(0)
	v_mfma_f32_16x16x32_bf16 v[32:35], v[44:47], v[124:127], v[140:143]
	s_mov_b32 m0, s55
	v_lshl_add_u64 v[246:247], s[2:3], 0, v[76:77]
	v_lshl_add_u64 v[246:247], v[246:247], 0, s[30:31]
	global_load_lds_dwordx4 v[246:247], off
	v_mfma_f32_16x16x32_bf16 v[36:39], v[44:47], v[128:131], v[36:39]
	s_mov_b32 m0, s56
	v_lshl_add_u64 v[246:247], s[2:3], 0, v[70:71]
	v_lshl_add_u64 v[246:247], v[246:247], 0, s[28:29]
	global_load_lds_dwordx4 v[246:247], off
	v_mfma_f32_16x16x32_bf16 v[40:43], v[44:47], v[132:135], v[40:43]
	s_mov_b32 m0, s57
	v_lshl_add_u64 v[246:247], s[2:3], 0, v[78:79]
	v_lshl_add_u64 v[246:247], v[246:247], 0, s[30:31]
	global_load_lds_dwordx4 v[246:247], off
	v_mfma_f32_16x16x32_bf16 v[44:47], v[44:47], v[136:139], v[48:51]
	s_mov_b32 m0, s58
	v_lshl_add_u64 v[246:247], s[2:3], 0, v[72:73]
	v_lshl_add_u64 v[246:247], v[246:247], 0, s[28:29]
	global_load_lds_dwordx4 v[246:247], off
	v_mfma_f32_16x16x32_bf16 v[48:51], v[116:119], v[124:127], v[120:123]
	s_mov_b32 m0, s59
	v_lshl_add_u64 v[246:247], s[2:3], 0, v[80:81]
	v_lshl_add_u64 v[246:247], v[246:247], 0, s[30:31]
	global_load_lds_dwordx4 v[246:247], off
	v_mfma_f32_16x16x32_bf16 v[52:55], v[116:119], v[128:131], v[52:55]
	v_mfma_f32_16x16x32_bf16 v[56:59], v[116:119], v[132:135], v[56:59]
	v_mfma_f32_16x16x32_bf16 v[60:63], v[116:119], v[136:139], v[60:63]
	s_branch .LBB0_1258
.Lge6_last0:
	v_mfma_f32_16x16x32_bf16 v[20:23], v[28:31], v[128:131], v[20:23]
	v_mfma_f32_16x16x32_bf16 v[24:27], v[28:31], v[132:135], v[24:27]
	v_mfma_f32_16x16x32_bf16 v[28:31], v[28:31], v[136:139], v[32:35]
	s_waitcnt lgkmcnt(0)
	v_mfma_f32_16x16x32_bf16 v[32:35], v[44:47], v[124:127], v[140:143]
	v_mfma_f32_16x16x32_bf16 v[36:39], v[44:47], v[128:131], v[36:39]
	v_mfma_f32_16x16x32_bf16 v[40:43], v[44:47], v[132:135], v[40:43]
	v_mfma_f32_16x16x32_bf16 v[44:47], v[44:47], v[136:139], v[48:51]
	v_mfma_f32_16x16x32_bf16 v[48:51], v[116:119], v[124:127], v[120:123]
	v_mfma_f32_16x16x32_bf16 v[52:55], v[116:119], v[128:131], v[52:55]
	v_mfma_f32_16x16x32_bf16 v[56:59], v[116:119], v[132:135], v[56:59]
	v_mfma_f32_16x16x32_bf16 v[60:63], v[116:119], v[136:139], v[60:63]
	s_branch .LBB0_1258

; #define LAS __attribute__((address_space(3)))
; #define RUNP(N) do { if ((PHMASK >> N) & 1) { if ((PROBE_MASK >> N) & 1) { for (int r_ = 0; r_ < p.pad0; ++r_) { run_phase<N>(p, lds); SYNCG(); } } else run_phase<N>(p, lds); } } while (0)
; #define SYNCG() xcd_barrier(xb)
; __global__ void __launch_bounds__(256, 2) mega(Params p) {
;   extern __shared__ __attribute__((aligned(16))) char lds[];
;   volatile LAS unsigned* xst = (volatile LAS unsigned*)(lds + LDS_BYTES - 16);
;   if (threadIdx.x == 0) { xst[0] = 0u; xst[1] = 0u; }
;   __syncthreads();
;   const XcdBarrier xb = xcd_barrier_post((unsigned*)(p.ws + OFF_BAR), xst);
;   if (p.pad1) cg::this_grid().sync();
;   RUNP(0); SYNCG(); RUNP(1); SYNCG(); RUNP(2); SYNCG(); RUNP(3); SYNCG(); RUNP(4); SYNCG(); RUNP(5); SYNCG();
;   RUNP(6); SYNCG(); RUNP(7); SYNCG(); RUNP(8); SYNCG(); RUNP(9); SYNCG(); RUNP(10); SYNCG(); RUNP(11); RUNP(12); SYNCG();
;   RUNP(13); SYNCG(); RUNP(14); SYNCG(); RUNP(15); SYNCG(); RUNP(16); SYNCG(); RUNP(17);
; }
	.amdhsa_kernel _Z4mega6Params
		.amdhsa_group_segment_fixed_size 0
		.amdhsa_private_segment_fixed_size 0
		.amdhsa_kernarg_size 544
		.amdhsa_user_sgpr_count 2
		.amdhsa_user_sgpr_dispatch_ptr 0
		.amdhsa_user_sgpr_queue_ptr 0
		.amdhsa_user_sgpr_kernarg_segment_ptr 1
		.amdhsa_user_sgpr_dispatch_id 0
		.amdhsa_user_sgpr_kernarg_preload_length 0
		.amdhsa_user_sgpr_kernarg_preload_offset 0
		.amdhsa_user_sgpr_private_segment_size 0
		.amdhsa_uses_dynamic_stack 0
		.amdhsa_enable_private_segment 0
		.amdhsa_system_sgpr_workgroup_id_x 1
		.amdhsa_system_sgpr_workgroup_id_y 0
		.amdhsa_system_sgpr_workgroup_id_z 0
		.amdhsa_system_sgpr_workgroup_info 0
		.amdhsa_system_vgpr_workitem_id 2
		.amdhsa_next_free_vgpr 256
		.amdhsa_next_free_sgpr 102
		.amdhsa_accum_offset 256
		.amdhsa_reserve_vcc 1
		.amdhsa_float_round_mode_32 0
		.amdhsa_float_round_mode_16_64 0
		.amdhsa_float_denorm_mode_32 3
		.amdhsa_float_denorm_mode_16_64 3
		.amdhsa_dx10_clamp 1
		.amdhsa_ieee_mode 1
		.amdhsa_fp16_overflow 0
		.amdhsa_tg_split 0
		.amdhsa_exception_fp_ieee_invalid_op 0
		.amdhsa_exception_fp_denorm_src 0
		.amdhsa_exception_fp_ieee_div_zero 0
		.amdhsa_exception_fp_ieee_overflow 0
		.amdhsa_exception_fp_ieee_underflow 0
		.amdhsa_exception_fp_ieee_inexact 0
		.amdhsa_exception_int_div_zero 0
	.end_amdhsa_kernel

; #define LAS __attribute__((address_space(3)))
; #define RUNP(N) do { if ((PHMASK >> N) & 1) { if ((PROBE_MASK >> N) & 1) { for (int r_ = 0; r_ < p.pad0; ++r_) { run_phase<N>(p, lds); SYNCG(); } } else run_phase<N>(p, lds); } } while (0)
; #define SYNCG() xcd_barrier(xb)
; __global__ void __launch_bounds__(256, 2) mega(Params p) {
;   extern __shared__ __attribute__((aligned(16))) char lds[];
;   volatile LAS unsigned* xst = (volatile LAS unsigned*)(lds + LDS_BYTES - 16);
;   if (threadIdx.x == 0) { xst[0] = 0u; xst[1] = 0u; }
;   __syncthreads();
;   const XcdBarrier xb = xcd_barrier_post((unsigned*)(p.ws + OFF_BAR), xst);
;   if (p.pad1) cg::this_grid().sync();
;   RUNP(0); SYNCG(); RUNP(1); SYNCG(); RUNP(2); SYNCG(); RUNP(3); SYNCG(); RUNP(4); SYNCG(); RUNP(5); SYNCG();
;   RUNP(6); SYNCG(); RUNP(7); SYNCG(); RUNP(8); SYNCG(); RUNP(9); SYNCG(); RUNP(10); SYNCG(); RUNP(11); RUNP(12); SYNCG();
;   RUNP(13); SYNCG(); RUNP(14); SYNCG(); RUNP(15); SYNCG(); RUNP(16); SYNCG(); RUNP(17);
; }
amdhsa.kernels:
  - .agpr_count:     0
    .args:
      - .offset:         0
        .size:           288
        .value_kind:     by_value
      - .offset:         288
        .size:           4
        .value_kind:     hidden_block_count_x
      - .offset:         292
        .size:           4
        .value_kind:     hidden_block_count_y
      - .offset:         296
        .size:           4
        .value_kind:     hidden_block_count_z
      - .offset:         300
        .size:           2
        .value_kind:     hidden_group_size_x
      - .offset:         302
        .size:           2
        .value_kind:     hidden_group_size_y
      - .offset:         304
        .size:           2
        .value_kind:     hidden_group_size_z
      - .offset:         306
        .size:           2
        .value_kind:     hidden_remainder_x
      - .offset:         308
        .size:           2
        .value_kind:     hidden_remainder_y
      - .offset:         310
        .size:           2
        .value_kind:     hidden_remainder_z
      - .offset:         328
        .size:           8
        .value_kind:     hidden_global_offset_x
      - .offset:         336
        .size:           8
        .value_kind:     hidden_global_offset_y
      - .offset:         344
        .size:           8
        .value_kind:     hidden_global_offset_z
      - .offset:         352
        .size:           2
        .value_kind:     hidden_grid_dims
      - .offset:         376
        .size:           8
        .value_kind:     hidden_multigrid_sync_arg
      - .offset:         408
        .size:           4
        .value_kind:     hidden_dynamic_lds_size
    .group_segment_fixed_size: 0
    .kernarg_segment_align: 8
    .kernarg_segment_size: 544
    .language:       OpenCL C
    .language_version:
      - 2
      - 0
    .max_flat_workgroup_size: 256
    .name:           _Z4mega6Params
    .private_segment_fixed_size: 0
    .sgpr_count:     108
    .sgpr_spill_count: 90
    .symbol:         _Z4mega6Params.kd
    .uniform_work_group_size: 1
    .uses_dynamic_stack: false
    .vgpr_count:     256
    .vgpr_spill_count: 0
    .wavefront_size: 64
